# write-through (sc1) on the ffn-up activation stores and the residual-stream stores: less dirty L2 for the barrier release fence
# speedup vs baseline: 1.0141x; 1.0073x over previous
.LBB0_924:
	s_or_b64 exec, exec, s[6:7]
	s_and_b32 s36, s35, 3
	s_cmp_eq_u32 s36, 0
	s_cselect_b64 s[8:9], -1, 0
	s_cmp_lt_i32 s35, 32
	v_cmp_ne_u32_e32 vcc, 0, v83
	s_cselect_b64 s[6:7], -1, 0
	s_or_b64 s[8:9], s[8:9], vcc
	s_waitcnt lgkmcnt(1)
	v_lshlrev_b32_e32 v77, 16, v70
	v_and_b32_e32 v78, 0xffff0000, v70
	v_lshlrev_b32_e32 v75, 16, v71
	v_and_b32_e32 v76, 0xffff0000, v71
	v_lshlrev_b32_e32 v71, 16, v72
	v_and_b32_e32 v72, 0xffff0000, v72
	v_lshlrev_b32_e32 v1, 16, v73
	v_and_b32_e32 v70, 0xffff0000, v73
	s_nor_b64 s[8:9], s[6:7], s[8:9]
	s_and_saveexec_b64 s[38:39], s[8:9]
	s_xor_b64 s[8:9], exec, s[38:39]
	s_or_saveexec_b64 s[8:9], s[8:9]
	s_waitcnt lgkmcnt(0)
	v_lshlrev_b32_e32 v118, 16, v66
	v_and_b32_e32 v115, 0xffff0000, v66
	v_lshlrev_b32_e32 v112, 16, v67
	v_and_b32_e32 v110, 0xffff0000, v67
	v_lshlrev_b32_e32 v108, 16, v68
	v_and_b32_e32 v104, 0xffff0000, v68
	v_lshlrev_b32_e32 v102, 16, v69
	v_and_b32_e32 v100, 0xffff0000, v69
	s_lshl_b32 s34, s35, 8
	v_lshl_add_u64 v[66:67], v[80:81], 1, s[0:1]
	s_xor_b64 exec, exec, s[8:9]
	s_cbranch_execz .LBB0_928
	s_waitcnt vmcnt(8)
	v_fma_f32 v68, v38, v122, v34
	v_fmac_f32_e32 v68, v42, v77
	v_fmac_f32_e32 v68, v50, v99
	v_mul_f32_e32 v69, 0xbfb8aa3b, v68
	v_exp_f32_e32 v69, v69
	v_fma_f32 v80, v39, v120, v35
	v_fmac_f32_e32 v80, v43, v78
	v_fmac_f32_e32 v80, v51, v98
	v_add_f32_e32 v69, 1.0, v69
	v_mul_f32_e32 v81, 0xbfb8aa3b, v80
	v_rcp_f32_e32 v69, v69
	v_exp_f32_e32 v81, v81
	s_waitcnt vmcnt(1)
	v_fma_f32 v73, v46, v123, v58
	v_fmac_f32_e32 v73, v54, v118
	v_mul_f32_e32 v68, v68, v69
	v_add_f32_e32 v69, 1.0, v81
	v_rcp_f32_e32 v69, v69
	v_fma_f32 v114, v41, v114, v37
	v_fmac_f32_e32 v73, v62, v89
	v_fmac_f32_e32 v114, v45, v76
	v_mul_f32_e32 v69, v80, v69
	v_fma_f32 v80, v40, v117, v36
	v_fmac_f32_e32 v80, v44, v75
	v_fmac_f32_e32 v80, v52, v96
	v_mul_f32_e32 v81, 0xbfb8aa3b, v80
	v_exp_f32_e32 v81, v81
	v_mul_f32_e32 v68, v73, v68
	v_fma_f32 v73, v47, v121, v59
	v_fmac_f32_e32 v114, v53, v94
	v_add_f32_e32 v81, 1.0, v81
	v_fmac_f32_e32 v73, v55, v115
	v_rcp_f32_e32 v81, v81
	v_mul_f32_e32 v117, 0xbfb8aa3b, v114
	v_fmac_f32_e32 v73, v63, v97
	v_exp_f32_e32 v117, v117
	v_mul_f32_e32 v69, v73, v69
	v_fma_f32 v73, v48, v119, v60
	v_fmac_f32_e32 v73, v56, v112
	v_fmac_f32_e32 v73, v64, v95
	v_mul_f32_e32 v80, v80, v81
	v_mul_f32_e32 v73, v73, v80
	v_add_f32_e32 v80, 1.0, v117
	v_rcp_f32_e32 v80, v80
	v_fma_f32 v111, v6, v111, v2
	v_fmac_f32_e32 v111, v10, v71
	v_fmac_f32_e32 v111, v18, v92
	v_mul_f32_e32 v80, v114, v80
	v_mul_f32_e32 v114, 0xbfb8aa3b, v111
	v_exp_f32_e32 v114, v114
	v_fma_f32 v81, v49, v116, v61
	v_fmac_f32_e32 v81, v57, v110
	v_fma_f32 v107, v7, v107, v3
	v_fmac_f32_e32 v81, v65, v93
	v_fmac_f32_e32 v107, v11, v72
	v_mul_f32_e32 v80, v81, v80
	s_waitcnt vmcnt(0)
	v_fma_f32 v81, v14, v113, v30
	v_add_f32_e32 v113, 1.0, v114
	v_fmac_f32_e32 v107, v19, v90
	v_rcp_f32_e32 v113, v113
	v_mul_f32_e32 v114, 0xbfb8aa3b, v107
	v_exp_f32_e32 v114, v114
	v_fmac_f32_e32 v81, v22, v108
	v_fmac_f32_e32 v81, v26, v91
	v_mul_f32_e32 v111, v111, v113
	v_mul_f32_e32 v81, v81, v111
	v_add_f32_e32 v111, 1.0, v114
	v_rcp_f32_e32 v111, v111
	v_fma_f32 v105, v8, v105, v4
	v_fmac_f32_e32 v105, v12, v1
	v_fmac_f32_e32 v105, v20, v87
	v_mul_f32_e32 v107, v107, v111
	v_mul_f32_e32 v111, 0xbfb8aa3b, v105
	v_exp_f32_e32 v111, v111
	v_fma_f32 v109, v15, v109, v31
	v_fmac_f32_e32 v109, v23, v104
	v_fma_f32 v101, v9, v101, v5
	v_fmac_f32_e32 v109, v27, v88
	v_fmac_f32_e32 v101, v13, v70
	v_mul_f32_e32 v107, v109, v107
	v_add_f32_e32 v109, 1.0, v111
	v_fmac_f32_e32 v101, v21, v85
	v_rcp_f32_e32 v109, v109
	v_mul_f32_e32 v111, 0xbfb8aa3b, v101
	v_exp_f32_e32 v111, v111
	v_fma_f32 v106, v16, v106, v32
	v_fmac_f32_e32 v106, v24, v102
	v_fmac_f32_e32 v106, v28, v86
	v_mul_f32_e32 v105, v105, v109
	v_mul_f32_e32 v105, v106, v105
	v_add_f32_e32 v106, 1.0, v111
	v_rcp_f32_e32 v106, v106
	v_fma_f32 v103, v17, v103, v33
	v_fmac_f32_e32 v103, v25, v100
	v_cvt_pk_bf16_f32 v120, v68, v69
	v_add_u32_e32 v68, s34, v83
	v_fmac_f32_e32 v103, v29, v84
	v_mul_f32_e32 v101, v101, v106
	v_mad_i64_i32 v[68:69], s[38:39], v68, s50, v[66:67]
	v_mul_f32_e32 v101, v103, v101
	v_cvt_pk_bf16_f32 v121, v73, v80
	v_cvt_pk_bf16_f32 v122, v81, v107
	v_cvt_pk_bf16_f32 v123, v105, v101
	global_store_dwordx4 v[68:69], v[120:123], off sc1

.LBB0_930:
	s_or_b64 exec, exec, s[8:9]
	s_waitcnt vmcnt(8)
	v_fma_f32 v77, v38, v77, v34
	v_fmac_f32_e32 v77, v42, v99
	v_fmac_f32_e32 v77, v50, v128
	v_mul_f32_e32 v113, 0xbfb8aa3b, v77
	v_exp_f32_e32 v113, v113
	v_fma_f32 v78, v39, v78, v35
	v_fmac_f32_e32 v78, v43, v98
	v_fmac_f32_e32 v78, v51, v123
	s_waitcnt vmcnt(1)
	v_fma_f32 v116, v46, v118, v58
	v_add_f32_e32 v113, 1.0, v113
	v_mul_f32_e32 v118, 0xbfb8aa3b, v78
	v_rcp_f32_e32 v113, v113
	v_exp_f32_e32 v118, v118
	v_fma_f32 v75, v40, v75, v36
	v_fmac_f32_e32 v75, v44, v96
	v_mul_f32_e32 v77, v77, v113
	v_add_f32_e32 v113, 1.0, v118
	v_rcp_f32_e32 v113, v113
	v_fmac_f32_e32 v75, v52, v117
	v_fma_f32 v115, v47, v115, v59
	v_fma_f32 v76, v41, v76, v37
	v_mul_f32_e32 v78, v78, v113
	v_mul_f32_e32 v113, 0xbfb8aa3b, v75
	v_exp_f32_e32 v113, v113
	v_fmac_f32_e32 v115, v55, v97
	v_fmac_f32_e32 v76, v45, v94
	v_fmac_f32_e32 v115, v63, v120
	v_add_f32_e32 v113, 1.0, v113
	v_fmac_f32_e32 v76, v53, v111
	v_mul_f32_e32 v78, v115, v78
	v_rcp_f32_e32 v113, v113
	v_mul_f32_e32 v115, 0xbfb8aa3b, v76
	v_exp_f32_e32 v115, v115
	v_fma_f32 v112, v48, v112, v60
	v_fmac_f32_e32 v112, v56, v95
	v_fmac_f32_e32 v112, v64, v114
	v_mul_f32_e32 v75, v75, v113
	v_mul_f32_e32 v75, v112, v75
	v_add_f32_e32 v112, 1.0, v115
	v_rcp_f32_e32 v112, v112
	v_fma_f32 v71, v6, v71, v2
	v_fmac_f32_e32 v71, v10, v92
	v_fmac_f32_e32 v71, v18, v107
	v_mul_f32_e32 v76, v76, v112
	v_mul_f32_e32 v112, 0xbfb8aa3b, v71
	v_exp_f32_e32 v112, v112
	v_fma_f32 v110, v49, v110, v61
	v_fmac_f32_e32 v110, v57, v93
	v_fma_f32 v72, v7, v72, v3
	v_fmac_f32_e32 v110, v65, v109
	v_fmac_f32_e32 v72, v11, v90
	v_mul_f32_e32 v76, v110, v76
	v_add_f32_e32 v110, 1.0, v112
	v_fmac_f32_e32 v72, v19, v103
	v_rcp_f32_e32 v110, v110
	v_mul_f32_e32 v112, 0xbfb8aa3b, v72
	v_exp_f32_e32 v112, v112
	s_waitcnt vmcnt(0)
	v_fma_f32 v108, v14, v108, v30
	v_fmac_f32_e32 v108, v22, v91
	v_fmac_f32_e32 v108, v26, v105
	v_mul_f32_e32 v71, v71, v110
	v_mul_f32_e32 v71, v108, v71
	v_add_f32_e32 v108, 1.0, v112
	v_rcp_f32_e32 v108, v108
	v_fma_f32 v1, v8, v1, v4
	v_fmac_f32_e32 v1, v12, v87
	v_fmac_f32_e32 v1, v20, v81
	v_mul_f32_e32 v72, v72, v108
	v_mul_f32_e32 v108, 0xbfb8aa3b, v1
	v_exp_f32_e32 v108, v108
	v_fma_f32 v104, v15, v104, v31
	v_fmac_f32_e32 v104, v23, v88
	v_fma_f32 v70, v9, v70, v5
	v_fmac_f32_e32 v104, v27, v101
	v_fmac_f32_e32 v70, v13, v85
	v_mul_f32_e32 v72, v104, v72
	v_add_f32_e32 v104, 1.0, v108
	v_fmac_f32_e32 v70, v21, v73
	v_rcp_f32_e32 v104, v104
	v_mul_f32_e32 v108, 0xbfb8aa3b, v70
	v_exp_f32_e32 v108, v108
	v_fma_f32 v102, v16, v102, v32
	v_fmac_f32_e32 v102, v24, v86
	v_fmac_f32_e32 v102, v28, v80
	v_mul_f32_e32 v1, v1, v104
	v_mul_f32_e32 v1, v102, v1
	v_add_f32_e32 v102, 1.0, v108
	v_rcp_f32_e32 v102, v102
	v_fma_f32 v100, v17, v100, v33
	v_fmac_f32_e32 v100, v25, v84
	v_fmac_f32_e32 v100, v29, v69
	v_mul_f32_e32 v70, v70, v102
	v_fmac_f32_e32 v116, v54, v89
	v_mul_f32_e32 v70, v100, v70
	v_cvt_pk_bf16_f32 v149, v1, v70
	v_add_u32_e32 v1, s34, v106
	v_fmac_f32_e32 v116, v62, v126
	v_cvt_pk_bf16_f32 v148, v71, v72
	v_mad_i64_i32 v[70:71], s[8:9], v1, s50, v[66:67]
	v_or_b32_e32 v1, 2, v83
	v_mul_f32_e32 v77, v116, v77
	v_cvt_pk_bf16_f32 v146, v77, v78
	v_cvt_pk_bf16_f32 v147, v75, v76
	global_store_dwordx4 v[70:71], v[146:149], off sc1
	v_cmp_gt_i32_e32 vcc, s46, v1
	v_mov_b32_e32 v121, 0
	v_mov_b32_e32 v115, 0
	v_mov_b32_e32 v110, 0
	v_mov_b32_e32 v106, 0
	v_mov_b32_e32 v102, 0
	v_mov_b32_e32 v76, 0
	v_mov_b32_e32 v70, 0
	v_mov_b32_e32 v129, 0
	v_mov_b32_e32 v124, 0
	v_mov_b32_e32 v118, 0
	v_mov_b32_e32 v112, 0
	v_mov_b32_e32 v108, 0
	v_mov_b32_e32 v104, 0
	v_mov_b32_e32 v100, 0
	v_mov_b32_e32 v72, 0
	s_and_saveexec_b64 s[8:9], vcc
	s_cbranch_execz .LBB0_932
	v_mul_lo_u32 v68, v1, s51
	v_add3_u32 v68, 0, v68, v79
	ds_read_b128 v[146:149], v68 offset:528
	ds_read_b128 v[150:153], v68 offset:656
	s_waitcnt lgkmcnt(1)
	v_lshlrev_b32_e32 v129, 16, v146
	v_and_b32_e32 v124, 0xffff0000, v146
	v_lshlrev_b32_e32 v118, 16, v147
	v_and_b32_e32 v112, 0xffff0000, v147
	v_lshlrev_b32_e32 v108, 16, v148
	v_and_b32_e32 v104, 0xffff0000, v148
	v_lshlrev_b32_e32 v100, 16, v149
	v_and_b32_e32 v72, 0xffff0000, v149
	s_waitcnt lgkmcnt(0)
	v_lshlrev_b32_e32 v68, 16, v150
	v_and_b32_e32 v121, 0xffff0000, v150
	v_lshlrev_b32_e32 v115, 16, v151
	v_and_b32_e32 v110, 0xffff0000, v151
	v_lshlrev_b32_e32 v106, 16, v152
	v_and_b32_e32 v102, 0xffff0000, v152
	v_lshlrev_b32_e32 v76, 16, v153
	v_and_b32_e32 v70, 0xffff0000, v153
.LBB0_932:
	s_or_b64 exec, exec, s[8:9]
	v_fma_f32 v71, v38, v99, v34
	v_fmac_f32_e32 v71, v42, v128
	v_fmac_f32_e32 v71, v50, v129
	v_mul_f32_e32 v75, 0xbfb8aa3b, v71
	v_exp_f32_e32 v75, v75
	v_fma_f32 v78, v39, v98, v35
	v_fmac_f32_e32 v78, v43, v123
	v_fmac_f32_e32 v78, v51, v124
	v_fma_f32 v77, v46, v89, v58
	v_add_f32_e32 v75, 1.0, v75
	v_mul_f32_e32 v89, 0xbfb8aa3b, v78
	v_rcp_f32_e32 v75, v75
	v_exp_f32_e32 v89, v89
	v_fmac_f32_e32 v77, v54, v126
	v_fmac_f32_e32 v77, v62, v68
	v_mul_f32_e32 v71, v71, v75
	v_add_f32_e32 v75, 1.0, v89
	v_rcp_f32_e32 v75, v75
	v_mul_f32_e32 v71, v77, v71
	v_fma_f32 v77, v47, v97, v59
	v_fma_f32 v94, v41, v94, v37
	v_mul_f32_e32 v75, v78, v75
	v_fma_f32 v78, v40, v96, v36
	v_fmac_f32_e32 v78, v44, v117
	v_fmac_f32_e32 v78, v52, v118
	v_mul_f32_e32 v89, 0xbfb8aa3b, v78
	v_exp_f32_e32 v89, v89
	v_fmac_f32_e32 v77, v55, v120
	v_fmac_f32_e32 v94, v45, v111
	v_fmac_f32_e32 v77, v63, v121
	v_add_f32_e32 v89, 1.0, v89
	v_fmac_f32_e32 v94, v53, v112
	v_mul_f32_e32 v75, v77, v75
	v_fma_f32 v77, v48, v95, v60
	v_rcp_f32_e32 v89, v89
	v_mul_f32_e32 v95, 0xbfb8aa3b, v94
	v_exp_f32_e32 v95, v95
	v_fmac_f32_e32 v77, v56, v114
	v_fma_f32 v92, v6, v92, v2
	v_fmac_f32_e32 v77, v64, v115
	v_mul_f32_e32 v78, v78, v89
	v_fmac_f32_e32 v92, v10, v107
	v_mul_f32_e32 v77, v77, v78
	v_add_f32_e32 v78, 1.0, v95
	v_fmac_f32_e32 v92, v18, v108
	v_rcp_f32_e32 v78, v78
	v_fma_f32 v89, v49, v93, v61
	v_mul_f32_e32 v93, 0xbfb8aa3b, v92
	v_exp_f32_e32 v93, v93
	v_fmac_f32_e32 v89, v57, v109
	v_fma_f32 v90, v7, v90, v3
	v_fmac_f32_e32 v89, v65, v110
	v_mul_f32_e32 v78, v94, v78
	v_fmac_f32_e32 v90, v11, v103
	v_mul_f32_e32 v78, v89, v78
	v_fma_f32 v89, v14, v91, v30
	v_add_f32_e32 v91, 1.0, v93
	v_fmac_f32_e32 v90, v19, v104
	v_rcp_f32_e32 v91, v91
	v_mul_f32_e32 v93, 0xbfb8aa3b, v90
	v_exp_f32_e32 v93, v93
	v_fmac_f32_e32 v89, v22, v105
	v_fmac_f32_e32 v89, v26, v106
	v_mul_f32_e32 v91, v92, v91
	v_mul_f32_e32 v89, v89, v91
	v_add_f32_e32 v91, 1.0, v93
	v_rcp_f32_e32 v91, v91
	v_fma_f32 v87, v8, v87, v4
	v_fmac_f32_e32 v87, v12, v81
	v_fmac_f32_e32 v87, v20, v100
	v_mul_f32_e32 v90, v90, v91
	v_mul_f32_e32 v91, 0xbfb8aa3b, v87
	v_exp_f32_e32 v91, v91
	v_fma_f32 v88, v15, v88, v31
	v_fmac_f32_e32 v88, v23, v101
	v_fma_f32 v85, v9, v85, v5
	v_fmac_f32_e32 v88, v27, v102
	v_fmac_f32_e32 v85, v13, v73
	v_mul_f32_e32 v88, v88, v90
	v_add_f32_e32 v90, 1.0, v91
	v_fmac_f32_e32 v85, v21, v72
	v_rcp_f32_e32 v90, v90
	v_mul_f32_e32 v91, 0xbfb8aa3b, v85
	v_exp_f32_e32 v91, v91
	v_fma_f32 v86, v16, v86, v32
	v_fmac_f32_e32 v86, v24, v80
	v_fmac_f32_e32 v86, v28, v76
	v_mul_f32_e32 v87, v87, v90
	v_mul_f32_e32 v87, v86, v87
	v_add_f32_e32 v86, 1.0, v91
	v_rcp_f32_e32 v86, v86
	v_fma_f32 v84, v17, v84, v33
	v_fmac_f32_e32 v84, v25, v69
	v_fmac_f32_e32 v84, v29, v70
	v_mul_f32_e32 v85, v85, v86
	v_add_u32_e32 v1, s34, v1
	v_mul_f32_e32 v90, v84, v85
	v_cvt_pk_bf16_f32 v84, v71, v75
	v_cvt_pk_bf16_f32 v85, v77, v78
	v_cvt_pk_bf16_f32 v86, v89, v88
	v_mad_i64_i32 v[88:89], s[8:9], v1, s50, v[66:67]
	v_or_b32_e32 v78, 3, v83
	v_cvt_pk_bf16_f32 v87, v87, v90
	global_store_dwordx4 v[88:89], v[84:87], off sc1
	v_cmp_gt_i32_e32 vcc, s46, v78
	v_mov_b32_e32 v1, 0
	v_mov_b32_e32 v127, 0
	v_mov_b32_e32 v122, 0
	v_mov_b32_e32 v116, 0
	v_mov_b32_e32 v97, 0
	v_mov_b32_e32 v91, 0
	v_mov_b32_e32 v85, 0
	v_mov_b32_e32 v77, 0
	v_mov_b32_e32 v71, 0
	v_mov_b32_e32 v134, 0
	v_mov_b32_e32 v125, 0
	v_mov_b32_e32 v119, 0
	v_mov_b32_e32 v113, 0
	v_mov_b32_e32 v95, 0
	v_mov_b32_e32 v89, 0
	v_mov_b32_e32 v84, 0
	v_mov_b32_e32 v75, 0
	s_and_saveexec_b64 s[8:9], vcc
	s_cbranch_execz .LBB0_934
	v_mul_lo_u32 v71, v78, s51
	v_add3_u32 v71, 0, v71, v79
	ds_read_b128 v[84:87], v71 offset:528
	ds_read_b128 v[90:93], v71 offset:656
	s_waitcnt lgkmcnt(1)
	v_lshlrev_b32_e32 v134, 16, v84
	v_and_b32_e32 v125, 0xffff0000, v84
	v_lshlrev_b32_e32 v119, 16, v85
	v_and_b32_e32 v113, 0xffff0000, v85
	v_lshlrev_b32_e32 v95, 16, v86
	v_and_b32_e32 v89, 0xffff0000, v86
	v_lshlrev_b32_e32 v84, 16, v87
	v_and_b32_e32 v75, 0xffff0000, v87
	s_waitcnt lgkmcnt(0)
	v_lshlrev_b32_e32 v127, 16, v90
	v_and_b32_e32 v122, 0xffff0000, v90
	v_lshlrev_b32_e32 v116, 16, v91
	v_and_b32_e32 v97, 0xffff0000, v91
	v_lshlrev_b32_e32 v91, 16, v92
	v_and_b32_e32 v85, 0xffff0000, v92
	v_lshlrev_b32_e32 v77, 16, v93
	v_and_b32_e32 v71, 0xffff0000, v93
.LBB0_934:
	s_or_b64 exec, exec, s[8:9]
	v_fma_f32 v86, v38, v128, v34
	v_fmac_f32_e32 v86, v42, v129
	v_fmac_f32_e32 v86, v50, v134
	v_mul_f32_e32 v87, 0xbfb8aa3b, v86
	v_exp_f32_e32 v87, v87
	v_fma_f32 v90, v39, v123, v35
	v_fmac_f32_e32 v90, v43, v124
	v_fmac_f32_e32 v90, v51, v125
	v_add_f32_e32 v87, 1.0, v87
	v_mul_f32_e32 v92, 0xbfb8aa3b, v90
	v_rcp_f32_e32 v87, v87
	v_exp_f32_e32 v92, v92
	v_fma_f32 v88, v46, v126, v58
	v_fmac_f32_e32 v88, v54, v68
	v_mul_f32_e32 v86, v86, v87
	v_add_f32_e32 v87, 1.0, v92
	v_rcp_f32_e32 v87, v87
	v_fma_f32 v93, v41, v111, v37
	v_fmac_f32_e32 v88, v62, v127
	v_fmac_f32_e32 v93, v45, v112
	v_mul_f32_e32 v87, v90, v87
	v_fma_f32 v90, v40, v117, v36
	v_fmac_f32_e32 v90, v44, v118
	v_fmac_f32_e32 v90, v52, v119
	v_mul_f32_e32 v92, 0xbfb8aa3b, v90
	v_exp_f32_e32 v92, v92
	v_mul_f32_e32 v86, v88, v86
	v_fma_f32 v88, v47, v120, v59
	v_fmac_f32_e32 v93, v53, v113
	v_add_f32_e32 v92, 1.0, v92
	v_fmac_f32_e32 v88, v55, v121
	v_rcp_f32_e32 v92, v92
	v_mul_f32_e32 v94, 0xbfb8aa3b, v93
	v_fmac_f32_e32 v88, v63, v122
	v_exp_f32_e32 v94, v94
	v_mul_f32_e32 v87, v88, v87
	v_fma_f32 v88, v48, v114, v60
	v_fmac_f32_e32 v88, v56, v115
	v_fmac_f32_e32 v88, v64, v116
	v_mul_f32_e32 v90, v90, v92
	v_mul_f32_e32 v88, v88, v90
	v_add_f32_e32 v90, 1.0, v94
	v_rcp_f32_e32 v90, v90
	v_fma_f32 v96, v7, v103, v3
	v_fmac_f32_e32 v96, v11, v104
	v_fma_f32 v92, v49, v109, v61
	v_mul_f32_e32 v90, v93, v90
	v_fma_f32 v93, v6, v107, v2
	v_fmac_f32_e32 v93, v10, v108
	v_fmac_f32_e32 v93, v18, v95
	v_mul_f32_e32 v94, 0xbfb8aa3b, v93
	v_exp_f32_e32 v94, v94
	v_fmac_f32_e32 v96, v19, v89
	v_fmac_f32_e32 v92, v57, v110
	v_mul_f32_e32 v98, 0xbfb8aa3b, v96
	v_add_f32_e32 v94, 1.0, v94
	v_rcp_f32_e32 v94, v94
	v_fmac_f32_e32 v92, v65, v97
	v_exp_f32_e32 v98, v98
	v_mul_f32_e32 v90, v92, v90
	v_fma_f32 v92, v14, v105, v30
	v_fmac_f32_e32 v92, v22, v106
	v_fmac_f32_e32 v92, v26, v91
	v_mul_f32_e32 v93, v93, v94
	v_mul_f32_e32 v92, v92, v93
	v_add_f32_e32 v93, 1.0, v98
	v_rcp_f32_e32 v93, v93
	v_fma_f32 v81, v8, v81, v4
	v_fmac_f32_e32 v81, v12, v100
	v_fmac_f32_e32 v81, v20, v84
	v_mul_f32_e32 v93, v96, v93
	v_mul_f32_e32 v96, 0xbfb8aa3b, v81
	v_exp_f32_e32 v96, v96
	v_fma_f32 v94, v15, v101, v31
	v_fmac_f32_e32 v94, v23, v102
	v_fma_f32 v73, v9, v73, v5
	v_fmac_f32_e32 v94, v27, v85
	v_fmac_f32_e32 v73, v13, v72
	v_mul_f32_e32 v93, v94, v93
	v_add_f32_e32 v94, 1.0, v96
	v_fmac_f32_e32 v73, v21, v75
	v_rcp_f32_e32 v94, v94
	v_mul_f32_e32 v96, 0xbfb8aa3b, v73
	v_exp_f32_e32 v96, v96
	v_fma_f32 v80, v16, v80, v32
	v_fmac_f32_e32 v80, v24, v76
	v_fmac_f32_e32 v80, v28, v77
	v_mul_f32_e32 v81, v81, v94
	v_mul_f32_e32 v80, v80, v81
	v_add_f32_e32 v81, 1.0, v96
	v_rcp_f32_e32 v81, v81
	v_fma_f32 v69, v17, v69, v33
	v_fmac_f32_e32 v69, v25, v70
	v_fmac_f32_e32 v69, v29, v71
	v_mul_f32_e32 v73, v73, v81
	v_mul_f32_e32 v69, v69, v73
	v_cvt_pk_bf16_f32 v149, v80, v69
	v_add_u32_e32 v69, s34, v78
	v_mad_i64_i32 v[80:81], s[8:9], v69, s50, v[66:67]
	v_cvt_pk_bf16_f32 v146, v86, v87
	v_cvt_pk_bf16_f32 v147, v88, v90
	v_cvt_pk_bf16_f32 v148, v92, v93
	global_store_dwordx4 v[80:81], v[146:149], off sc1
	v_or_b32_e32 v80, 4, v83
	v_cmp_gt_i32_e32 vcc, s46, v80
	v_mov_b32_e32 v107, 0
	v_mov_b32_e32 v103, 0
	v_mov_b32_e32 v98, 0
	v_mov_b32_e32 v92, 0
	v_mov_b32_e32 v86, 0
	v_mov_b32_e32 v78, 0
	v_mov_b32_e32 v69, 0
	v_mov_b32_e32 v114, 0
	v_mov_b32_e32 v111, 0
	v_mov_b32_e32 v105, 0
	v_mov_b32_e32 v101, 0
	v_mov_b32_e32 v96, 0
	v_mov_b32_e32 v90, 0
	v_mov_b32_e32 v81, 0
	v_mov_b32_e32 v73, 0
	s_and_saveexec_b64 s[8:9], vcc
	s_cbranch_execz .LBB0_936
	v_mul_lo_u32 v1, v80, s51
	v_add3_u32 v1, 0, v1, v79
	ds_read_b128 v[146:149], v1 offset:528
	ds_read_b128 v[150:153], v1 offset:656
	s_waitcnt lgkmcnt(1)
	v_lshlrev_b32_e32 v114, 16, v146
	v_and_b32_e32 v111, 0xffff0000, v146
	v_lshlrev_b32_e32 v105, 16, v147
	v_and_b32_e32 v101, 0xffff0000, v147
	v_lshlrev_b32_e32 v96, 16, v148
	v_and_b32_e32 v90, 0xffff0000, v148
	v_lshlrev_b32_e32 v81, 16, v149
	v_and_b32_e32 v73, 0xffff0000, v149
	s_waitcnt lgkmcnt(0)
	v_lshlrev_b32_e32 v1, 16, v150
	v_and_b32_e32 v107, 0xffff0000, v150
	v_lshlrev_b32_e32 v103, 16, v151
	v_and_b32_e32 v98, 0xffff0000, v151
	v_lshlrev_b32_e32 v92, 16, v152
	v_and_b32_e32 v86, 0xffff0000, v152
	v_lshlrev_b32_e32 v78, 16, v153
	v_and_b32_e32 v69, 0xffff0000, v153
.LBB0_936:
	s_or_b64 exec, exec, s[8:9]
	v_fma_f32 v87, v38, v129, v34
	v_fmac_f32_e32 v87, v42, v134
	v_fmac_f32_e32 v87, v50, v114
	v_mul_f32_e32 v88, 0xbfb8aa3b, v87
	v_exp_f32_e32 v88, v88
	v_fma_f32 v93, v39, v124, v35
	v_fmac_f32_e32 v93, v43, v125
	v_fmac_f32_e32 v93, v51, v111
	v_add_f32_e32 v88, 1.0, v88
	v_rcp_f32_e32 v88, v88
	v_mul_f32_e32 v94, 0xbfb8aa3b, v93
	v_exp_f32_e32 v94, v94
	v_fma_f32 v68, v46, v68, v58
	v_fmac_f32_e32 v68, v54, v127
	v_fmac_f32_e32 v68, v62, v1
	v_mul_f32_e32 v87, v87, v88
	v_mul_f32_e32 v68, v68, v87
	v_add_f32_e32 v87, 1.0, v94
	v_rcp_f32_e32 v87, v87
	v_fma_f32 v99, v41, v112, v37
	v_fmac_f32_e32 v99, v45, v113
	v_fma_f32 v88, v47, v121, v59
	v_mul_f32_e32 v87, v93, v87
	v_fma_f32 v93, v40, v118, v36
	v_fmac_f32_e32 v93, v44, v119
	v_fmac_f32_e32 v93, v52, v105
	v_mul_f32_e32 v94, 0xbfb8aa3b, v93
	v_exp_f32_e32 v94, v94
	v_fmac_f32_e32 v99, v53, v101
	v_fmac_f32_e32 v88, v55, v122
	v_mul_f32_e32 v109, 0xbfb8aa3b, v99
	v_add_f32_e32 v94, 1.0, v94
	v_rcp_f32_e32 v94, v94
	v_fmac_f32_e32 v88, v63, v107
	v_exp_f32_e32 v109, v109
	v_mul_f32_e32 v87, v88, v87
	v_fma_f32 v88, v48, v115, v60
	v_fmac_f32_e32 v88, v56, v116
	v_fmac_f32_e32 v88, v64, v103
	v_mul_f32_e32 v93, v93, v94
	v_mul_f32_e32 v88, v88, v93
	v_add_f32_e32 v93, 1.0, v109
	v_rcp_f32_e32 v93, v93
	v_fma_f32 v94, v49, v110, v61
	v_fmac_f32_e32 v94, v57, v97
	v_fma_f32 v104, v7, v104, v3
	v_mul_f32_e32 v93, v99, v93
	v_fma_f32 v99, v6, v108, v2
	v_fmac_f32_e32 v99, v10, v95
	v_fmac_f32_e32 v99, v18, v96
	v_mul_f32_e32 v108, 0xbfb8aa3b, v99
	v_exp_f32_e32 v108, v108
	v_fmac_f32_e32 v94, v65, v98
	v_fmac_f32_e32 v104, v11, v89
	v_mul_f32_e32 v93, v94, v93
	v_fma_f32 v94, v14, v106, v30
	v_add_f32_e32 v106, 1.0, v108
	v_fmac_f32_e32 v104, v19, v90
	v_rcp_f32_e32 v106, v106
	v_mul_f32_e32 v108, 0xbfb8aa3b, v104
	v_exp_f32_e32 v108, v108
	v_fmac_f32_e32 v94, v22, v91
	v_fmac_f32_e32 v94, v26, v92
	v_mul_f32_e32 v99, v99, v106
	v_mul_f32_e32 v94, v94, v99
	v_add_f32_e32 v99, 1.0, v108
	v_rcp_f32_e32 v99, v99
	v_fma_f32 v100, v8, v100, v4
	v_fmac_f32_e32 v100, v12, v84
	v_fmac_f32_e32 v100, v20, v81
	v_mul_f32_e32 v99, v104, v99
	v_mul_f32_e32 v104, 0xbfb8aa3b, v100
	v_exp_f32_e32 v104, v104
	v_fma_f32 v102, v15, v102, v31
	v_fmac_f32_e32 v102, v23, v85
	v_fma_f32 v72, v9, v72, v5
	v_fmac_f32_e32 v102, v27, v86
	v_fmac_f32_e32 v72, v13, v75
	v_mul_f32_e32 v99, v102, v99
	v_add_f32_e32 v102, 1.0, v104
	v_fmac_f32_e32 v72, v21, v73
	v_rcp_f32_e32 v102, v102
	v_mul_f32_e32 v104, 0xbfb8aa3b, v72
	v_exp_f32_e32 v104, v104
	v_fma_f32 v76, v16, v76, v32
	v_fmac_f32_e32 v76, v24, v77
	v_fmac_f32_e32 v76, v28, v78
	v_mul_f32_e32 v100, v100, v102
	v_mul_f32_e32 v76, v76, v100
	v_add_f32_e32 v100, 1.0, v104
	v_rcp_f32_e32 v100, v100
	v_fma_f32 v70, v17, v70, v33
	v_fmac_f32_e32 v70, v25, v71
	v_fmac_f32_e32 v70, v29, v69
	v_mul_f32_e32 v72, v72, v100
	v_cvt_pk_bf16_f32 v146, v68, v87
	v_add_u32_e32 v68, s34, v80
	v_mul_f32_e32 v70, v70, v72
	v_mad_i64_i32 v[108:109], s[8:9], v68, s50, v[66:67]
	v_or_b32_e32 v112, 5, v83
	v_cvt_pk_bf16_f32 v147, v88, v93
	v_cvt_pk_bf16_f32 v148, v94, v99
	v_cvt_pk_bf16_f32 v149, v76, v70
	global_store_dwordx4 v[108:109], v[146:149], off sc1
	v_cmp_gt_i32_e32 vcc, s46, v112
	v_mov_b32_e32 v106, 0
	v_mov_b32_e32 v109, 0
	v_mov_b32_e32 v104, 0
	v_mov_b32_e32 v100, 0
	v_mov_b32_e32 v94, 0
	v_mov_b32_e32 v88, 0
	v_mov_b32_e32 v80, 0
	v_mov_b32_e32 v72, 0
	v_mov_b32_e32 v68, 0
	v_mov_b32_e32 v110, 0
	v_mov_b32_e32 v108, 0
	v_mov_b32_e32 v102, 0
	v_mov_b32_e32 v99, 0
	v_mov_b32_e32 v93, 0
	v_mov_b32_e32 v87, 0
	v_mov_b32_e32 v76, 0
	v_mov_b32_e32 v70, 0
	s_and_saveexec_b64 s[8:9], vcc
	s_cbranch_execz .LBB0_938
	v_mul_lo_u32 v68, v112, s51
	v_add3_u32 v68, 0, v68, v79
	ds_read_b128 v[146:149], v68 offset:528
	ds_read_b128 v[150:153], v68 offset:656
	s_waitcnt lgkmcnt(1)
	v_lshlrev_b32_e32 v110, 16, v146
	v_and_b32_e32 v108, 0xffff0000, v146
	v_lshlrev_b32_e32 v102, 16, v147
	v_and_b32_e32 v99, 0xffff0000, v147
	v_lshlrev_b32_e32 v93, 16, v148
	v_and_b32_e32 v87, 0xffff0000, v148
	v_lshlrev_b32_e32 v76, 16, v149
	v_and_b32_e32 v70, 0xffff0000, v149
	s_waitcnt lgkmcnt(0)
	v_lshlrev_b32_e32 v109, 16, v150
	v_and_b32_e32 v104, 0xffff0000, v150
	v_lshlrev_b32_e32 v100, 16, v151
	v_and_b32_e32 v94, 0xffff0000, v151
	v_lshlrev_b32_e32 v88, 16, v152
	v_and_b32_e32 v80, 0xffff0000, v152
	v_lshlrev_b32_e32 v72, 16, v153
	v_and_b32_e32 v68, 0xffff0000, v153
.LBB0_938:
	s_or_b64 exec, exec, s[8:9]
	v_fma_f32 v115, v38, v134, v34
	v_fmac_f32_e32 v115, v42, v114
	v_fmac_f32_e32 v115, v50, v110
	v_mul_f32_e32 v117, 0xbfb8aa3b, v115
	v_exp_f32_e32 v117, v117
	v_fma_f32 v120, v39, v125, v35
	v_fmac_f32_e32 v120, v43, v111
	v_fmac_f32_e32 v120, v51, v108
	v_add_f32_e32 v117, 1.0, v117
	v_mul_f32_e32 v121, 0xbfb8aa3b, v120
	v_rcp_f32_e32 v117, v117
	v_exp_f32_e32 v121, v121
	v_fma_f32 v119, v40, v119, v36
	v_fmac_f32_e32 v119, v44, v105
	v_mul_f32_e32 v115, v115, v117
	v_add_f32_e32 v117, 1.0, v121
	v_rcp_f32_e32 v117, v117
	v_fma_f32 v118, v46, v127, v58
	v_fmac_f32_e32 v119, v52, v102
	v_fmac_f32_e32 v118, v54, v1
	v_mul_f32_e32 v117, v120, v117
	v_mul_f32_e32 v120, 0xbfb8aa3b, v119
	v_fmac_f32_e32 v118, v62, v109
	v_exp_f32_e32 v120, v120
	v_mul_f32_e32 v115, v118, v115
	v_fma_f32 v118, v47, v122, v59
	v_fmac_f32_e32 v118, v55, v107
	v_fma_f32 v113, v41, v113, v37
	v_fmac_f32_e32 v118, v63, v104
	v_fmac_f32_e32 v113, v45, v101
	v_mul_f32_e32 v117, v118, v117
	v_add_f32_e32 v118, 1.0, v120
	v_fmac_f32_e32 v113, v53, v99
	v_rcp_f32_e32 v118, v118
	v_mul_f32_e32 v120, 0xbfb8aa3b, v113
	v_exp_f32_e32 v120, v120
	v_fma_f32 v116, v48, v116, v60
	v_fmac_f32_e32 v116, v56, v103
	v_fmac_f32_e32 v116, v64, v100
	v_mul_f32_e32 v118, v119, v118
	v_mul_f32_e32 v118, v116, v118
	v_add_f32_e32 v116, 1.0, v120
	v_rcp_f32_e32 v116, v116
	v_fma_f32 v95, v6, v95, v2
	v_fmac_f32_e32 v95, v10, v96
	v_fmac_f32_e32 v95, v18, v93
	v_mul_f32_e32 v113, v113, v116
	v_mul_f32_e32 v116, 0xbfb8aa3b, v95
	v_exp_f32_e32 v116, v116
	v_fma_f32 v97, v49, v97, v61
	v_fmac_f32_e32 v97, v57, v98
	v_fma_f32 v89, v7, v89, v3
	v_fmac_f32_e32 v97, v65, v94
	v_fmac_f32_e32 v89, v11, v90
	v_mul_f32_e32 v97, v97, v113
	v_add_f32_e32 v113, 1.0, v116
	v_fmac_f32_e32 v89, v19, v87
	v_rcp_f32_e32 v113, v113
	v_mul_f32_e32 v116, 0xbfb8aa3b, v89
	v_exp_f32_e32 v116, v116
	v_fma_f32 v91, v14, v91, v30
	v_fmac_f32_e32 v91, v22, v92
	v_fmac_f32_e32 v91, v26, v88
	v_mul_f32_e32 v95, v95, v113
	v_mul_f32_e32 v91, v91, v95
	v_add_f32_e32 v95, 1.0, v116
	v_rcp_f32_e32 v95, v95
	v_fma_f32 v84, v8, v84, v4
	v_fmac_f32_e32 v84, v12, v81
	v_fmac_f32_e32 v84, v20, v76
	v_mul_f32_e32 v89, v89, v95
	v_mul_f32_e32 v95, 0xbfb8aa3b, v84
	v_exp_f32_e32 v95, v95
	v_fma_f32 v85, v15, v85, v31
	v_fmac_f32_e32 v85, v23, v86
	v_fma_f32 v75, v9, v75, v5
	v_fmac_f32_e32 v85, v27, v80
	v_fmac_f32_e32 v75, v13, v73
	v_mul_f32_e32 v85, v85, v89
	v_add_f32_e32 v89, 1.0, v95
	v_fmac_f32_e32 v75, v21, v70
	v_rcp_f32_e32 v89, v89
	v_mul_f32_e32 v95, 0xbfb8aa3b, v75
	v_exp_f32_e32 v95, v95
	v_fma_f32 v77, v16, v77, v32
	v_fmac_f32_e32 v77, v24, v78
	v_fmac_f32_e32 v77, v28, v72
	v_mul_f32_e32 v84, v84, v89
	v_mul_f32_e32 v77, v77, v84
	v_add_f32_e32 v84, 1.0, v95
	v_rcp_f32_e32 v84, v84
	v_fma_f32 v71, v17, v71, v33
	v_fmac_f32_e32 v71, v25, v69
	v_fmac_f32_e32 v71, v29, v68
	v_mul_f32_e32 v75, v75, v84
	v_mul_f32_e32 v71, v71, v75
	v_cvt_pk_bf16_f32 v119, v77, v71
	v_add_u32_e32 v71, s34, v112
	v_cvt_pk_bf16_f32 v116, v115, v117
	v_cvt_pk_bf16_f32 v117, v118, v97
	v_cvt_pk_bf16_f32 v118, v91, v85
	v_mad_i64_i32 v[84:85], s[8:9], v71, s50, v[66:67]
	global_store_dwordx4 v[84:85], v[116:119], off sc1
	v_mov_b32_e32 v115, 0
	v_mov_b32_e32 v112, 0
	v_or_b32_e32 v118, 6, v83
	v_cmp_gt_i32_e32 vcc, s46, v118
	v_mov_b32_e32 v95, 0
	v_mov_b32_e32 v89, 0
	v_mov_b32_e32 v84, 0
	v_mov_b32_e32 v77, 0
	v_mov_b32_e32 v71, 0
	v_mov_b32_e32 v117, 0
	v_mov_b32_e32 v116, 0
	v_mov_b32_e32 v113, 0
	v_mov_b32_e32 v97, 0
	v_mov_b32_e32 v91, 0
	v_mov_b32_e32 v85, 0
	v_mov_b32_e32 v83, 0
	v_mov_b32_e32 v75, 0
	s_and_saveexec_b64 s[8:9], vcc
	s_cbranch_execz .LBB0_940
	v_mul_lo_u32 v71, v118, s51
	v_add3_u32 v71, 0, v71, v79
	ds_read_b128 v[120:123], v71 offset:528
	ds_read_b128 v[124:127], v71 offset:656
	s_waitcnt lgkmcnt(1)
	v_lshlrev_b32_e32 v117, 16, v120
	v_and_b32_e32 v116, 0xffff0000, v120
	v_lshlrev_b32_e32 v113, 16, v121
	v_and_b32_e32 v97, 0xffff0000, v121
	v_lshlrev_b32_e32 v91, 16, v122
	v_and_b32_e32 v85, 0xffff0000, v122
	v_lshlrev_b32_e32 v83, 16, v123
	v_and_b32_e32 v75, 0xffff0000, v123
	s_waitcnt lgkmcnt(0)
	v_lshlrev_b32_e32 v106, 16, v124
	v_and_b32_e32 v115, 0xffff0000, v124
	v_lshlrev_b32_e32 v112, 16, v125
	v_and_b32_e32 v95, 0xffff0000, v125
	v_lshlrev_b32_e32 v89, 16, v126
	v_and_b32_e32 v84, 0xffff0000, v126
	v_lshlrev_b32_e32 v77, 16, v127
	v_and_b32_e32 v71, 0xffff0000, v127
.LBB0_940:
	s_or_b64 exec, exec, s[8:9]
	v_fma_f32 v114, v38, v114, v34
	v_fmac_f32_e32 v114, v42, v110
	v_fmac_f32_e32 v114, v50, v117
	v_mul_f32_e32 v119, 0xbfb8aa3b, v114
	v_exp_f32_e32 v119, v119
	v_fma_f32 v111, v39, v111, v35
	v_fmac_f32_e32 v111, v43, v108
	v_fmac_f32_e32 v111, v51, v116
	v_add_f32_e32 v119, 1.0, v119
	v_rcp_f32_e32 v119, v119
	v_mul_f32_e32 v120, 0xbfb8aa3b, v111
	v_exp_f32_e32 v120, v120
	v_fma_f32 v1, v46, v1, v58
	v_fmac_f32_e32 v1, v54, v109
	v_fmac_f32_e32 v1, v62, v106
	v_mul_f32_e32 v114, v114, v119
	v_mul_f32_e32 v1, v1, v114
	v_add_f32_e32 v114, 1.0, v120
	v_rcp_f32_e32 v114, v114
	v_fma_f32 v105, v40, v105, v36
	v_fmac_f32_e32 v105, v44, v102
	v_fmac_f32_e32 v105, v52, v113
	v_mul_f32_e32 v111, v111, v114
	v_mul_f32_e32 v114, 0xbfb8aa3b, v105
	v_exp_f32_e32 v114, v114
	v_fma_f32 v107, v47, v107, v59
	v_fmac_f32_e32 v107, v55, v104
	v_fma_f32 v101, v41, v101, v37
	v_fmac_f32_e32 v107, v63, v115
	v_fmac_f32_e32 v101, v45, v99
	v_mul_f32_e32 v107, v107, v111
	v_add_f32_e32 v111, 1.0, v114
	v_fmac_f32_e32 v101, v53, v97
	v_rcp_f32_e32 v111, v111
	v_mul_f32_e32 v114, 0xbfb8aa3b, v101
	v_exp_f32_e32 v114, v114
	v_fma_f32 v103, v48, v103, v60
	v_fmac_f32_e32 v103, v56, v100
	v_fmac_f32_e32 v103, v64, v112
	v_mul_f32_e32 v105, v105, v111
	v_mul_f32_e32 v103, v103, v105
	v_add_f32_e32 v105, 1.0, v114
	v_rcp_f32_e32 v105, v105
	v_fma_f32 v96, v6, v96, v2
	v_fmac_f32_e32 v96, v10, v93
	v_fmac_f32_e32 v96, v18, v91
	v_mul_f32_e32 v101, v101, v105
	v_mul_f32_e32 v105, 0xbfb8aa3b, v96
	v_exp_f32_e32 v105, v105
	v_fma_f32 v98, v49, v98, v61
	v_fmac_f32_e32 v98, v57, v94
	v_fma_f32 v90, v7, v90, v3
	v_fmac_f32_e32 v98, v65, v95
	v_fmac_f32_e32 v90, v11, v87
	v_mul_f32_e32 v98, v98, v101
	v_add_f32_e32 v101, 1.0, v105
	v_fmac_f32_e32 v90, v19, v85
	v_rcp_f32_e32 v101, v101
	v_mul_f32_e32 v105, 0xbfb8aa3b, v90
	v_exp_f32_e32 v105, v105
	v_fma_f32 v92, v14, v92, v30
	v_fmac_f32_e32 v92, v22, v88
	v_fmac_f32_e32 v92, v26, v89
	v_mul_f32_e32 v96, v96, v101
	v_mul_f32_e32 v92, v92, v96
	v_add_f32_e32 v96, 1.0, v105
	v_rcp_f32_e32 v96, v96
	v_fma_f32 v81, v8, v81, v4
	v_fmac_f32_e32 v81, v12, v76
	v_fmac_f32_e32 v81, v20, v83
	v_mul_f32_e32 v90, v90, v96
	v_mul_f32_e32 v96, 0xbfb8aa3b, v81
	v_exp_f32_e32 v96, v96
	v_fma_f32 v86, v15, v86, v31
	v_fmac_f32_e32 v86, v23, v80
	v_fma_f32 v73, v9, v73, v5
	v_fmac_f32_e32 v86, v27, v84
	v_fmac_f32_e32 v73, v13, v70
	v_mul_f32_e32 v86, v86, v90
	v_add_f32_e32 v90, 1.0, v96
	v_fmac_f32_e32 v73, v21, v75
	v_rcp_f32_e32 v90, v90
	v_mul_f32_e32 v96, 0xbfb8aa3b, v73
	v_exp_f32_e32 v96, v96
	v_fma_f32 v78, v16, v78, v32
	v_fmac_f32_e32 v78, v24, v72
	v_fmac_f32_e32 v78, v28, v77
	v_mul_f32_e32 v81, v81, v90
	v_mul_f32_e32 v78, v78, v81
	v_add_f32_e32 v81, 1.0, v96
	v_rcp_f32_e32 v81, v81
	v_fma_f32 v69, v17, v69, v33
	v_fmac_f32_e32 v69, v25, v68
	v_fmac_f32_e32 v69, v29, v71
	v_mul_f32_e32 v73, v73, v81
	v_cvt_pk_bf16_f32 v120, v1, v107
	v_add_u32_e32 v1, s34, v118
	v_mul_f32_e32 v69, v69, v73
	v_mad_i64_i32 v[118:119], s[8:9], v1, s50, v[66:67]
	v_or_b32_e32 v1, 7, v82
	v_cvt_pk_bf16_f32 v121, v103, v98
	v_cvt_pk_bf16_f32 v122, v92, v86
	v_cvt_pk_bf16_f32 v123, v78, v69
	v_cmp_gt_i32_e32 vcc, s46, v1
	v_mov_b32_e32 v107, 0
	v_mov_b32_e32 v105, 0
	v_mov_b32_e32 v98, 0
	v_mov_b32_e32 v96, 0
	v_mov_b32_e32 v86, 0
	v_mov_b32_e32 v82, 0
	v_mov_b32_e32 v73, 0
	v_mov_b32_e32 v69, 0
	v_mov_b32_e32 v114, 0
	v_mov_b32_e32 v111, 0
	v_mov_b32_e32 v103, 0
	v_mov_b32_e32 v101, 0
	v_mov_b32_e32 v92, 0
	v_mov_b32_e32 v90, 0
	v_mov_b32_e32 v81, 0
	v_mov_b32_e32 v78, 0
	global_store_dwordx4 v[118:119], v[120:123], off sc1
	s_and_saveexec_b64 s[8:9], vcc
	s_cbranch_execz .LBB0_942
	v_mul_lo_u32 v69, v1, s51
	v_add3_u32 v69, 0, v69, v79
	ds_read_b128 v[118:121], v69 offset:528
	ds_read_b128 v[122:125], v69 offset:656
	s_waitcnt lgkmcnt(1)
	v_lshlrev_b32_e32 v114, 16, v118
	v_and_b32_e32 v111, 0xffff0000, v118
	v_lshlrev_b32_e32 v103, 16, v119
	v_and_b32_e32 v101, 0xffff0000, v119
	v_lshlrev_b32_e32 v92, 16, v120
	v_and_b32_e32 v90, 0xffff0000, v120
	v_lshlrev_b32_e32 v81, 16, v121
	v_and_b32_e32 v78, 0xffff0000, v121
	s_waitcnt lgkmcnt(0)
	v_lshlrev_b32_e32 v107, 16, v122
	v_and_b32_e32 v105, 0xffff0000, v122
	v_lshlrev_b32_e32 v98, 16, v123
	v_and_b32_e32 v96, 0xffff0000, v123
	v_lshlrev_b32_e32 v86, 16, v124
	v_and_b32_e32 v82, 0xffff0000, v124
	v_lshlrev_b32_e32 v73, 16, v125
	v_and_b32_e32 v69, 0xffff0000, v125
.LBB0_942:
	s_or_b64 exec, exec, s[8:9]
	s_cmp_eq_u32 s36, 3
	s_cselect_b64 s[8:9], -1, 0
	v_cmp_ne_u32_e32 vcc, s46, v1
	s_or_b64 s[8:9], s[8:9], vcc
	s_or_b64 s[36:37], s[6:7], s[8:9]
	s_and_saveexec_b64 s[8:9], s[36:37]
	s_cbranch_execz .LBB0_944
	v_fma_f32 v2, v6, v93, v2
	v_fmac_f32_e32 v2, v10, v91
	v_fmac_f32_e32 v2, v18, v92
	v_mul_f32_e32 v6, 0xbfb8aa3b, v2
	v_exp_f32_e32 v6, v6
	v_fma_f32 v34, v38, v110, v34
	v_fma_f32 v3, v7, v87, v3
	v_fmac_f32_e32 v34, v42, v117
	v_fmac_f32_e32 v3, v11, v85
	v_fmac_f32_e32 v34, v50, v114
	v_add_f32_e32 v6, 1.0, v6
	v_fmac_f32_e32 v3, v19, v90
	v_mul_f32_e32 v38, 0xbfb8aa3b, v34
	v_rcp_f32_e32 v6, v6
	v_mul_f32_e32 v7, 0xbfb8aa3b, v3
	v_exp_f32_e32 v38, v38
	v_exp_f32_e32 v7, v7
	v_fma_f32 v35, v39, v108, v35
	v_fma_f32 v14, v14, v88, v30
	v_fmac_f32_e32 v35, v43, v116
	v_fmac_f32_e32 v14, v22, v89
	v_fmac_f32_e32 v35, v51, v111
	v_fmac_f32_e32 v14, v26, v86
	v_mul_f32_e32 v2, v2, v6
	v_add_f32_e32 v38, 1.0, v38
	v_mul_f32_e32 v39, 0xbfb8aa3b, v35
	v_mul_f32_e32 v6, v14, v2
	v_add_f32_e32 v2, 1.0, v7
	v_rcp_f32_e32 v38, v38
	v_exp_f32_e32 v39, v39
	v_rcp_f32_e32 v2, v2
	v_fma_f32 v36, v40, v102, v36
	v_mul_f32_e32 v34, v34, v38
	v_add_f32_e32 v38, 1.0, v39
	v_mul_f32_e32 v2, v3, v2
	v_fma_f32 v3, v8, v76, v4
	v_rcp_f32_e32 v38, v38
	v_fmac_f32_e32 v3, v12, v83
	v_fmac_f32_e32 v3, v20, v81
	v_fmac_f32_e32 v36, v44, v113
	v_mul_f32_e32 v4, 0xbfb8aa3b, v3
	v_fmac_f32_e32 v36, v52, v103
	v_exp_f32_e32 v4, v4
	v_mul_f32_e32 v35, v35, v38
	v_mul_f32_e32 v38, 0xbfb8aa3b, v36
	v_exp_f32_e32 v38, v38
	v_fmac_f32_e32 v5, v9, v70
	v_fmac_f32_e32 v37, v41, v99
	v_fmac_f32_e32 v5, v13, v75
	v_fmac_f32_e32 v37, v45, v97
	v_fma_f32 v7, v15, v80, v31
	v_add_f32_e32 v4, 1.0, v4
	v_fmac_f32_e32 v5, v21, v78
	v_fmac_f32_e32 v37, v53, v101
	v_fmac_f32_e32 v7, v23, v84
	v_rcp_f32_e32 v4, v4
	v_mul_f32_e32 v8, 0xbfb8aa3b, v5
	v_add_f32_e32 v38, 1.0, v38
	v_mul_f32_e32 v40, 0xbfb8aa3b, v37
	v_fmac_f32_e32 v7, v27, v82
	v_exp_f32_e32 v8, v8
	v_rcp_f32_e32 v38, v38
	v_exp_f32_e32 v40, v40
	v_mul_f32_e32 v7, v7, v2
	v_fma_f32 v2, v16, v72, v32
	v_fmac_f32_e32 v2, v24, v77
	v_fmac_f32_e32 v2, v28, v73
	v_mul_f32_e32 v3, v3, v4
	v_mul_f32_e32 v9, v2, v3
	v_add_f32_e32 v2, 1.0, v8
	v_fma_f32 v39, v47, v104, v59
	v_mul_f32_e32 v36, v36, v38
	v_add_f32_e32 v38, 1.0, v40
	v_rcp_f32_e32 v2, v2
	v_fmac_f32_e32 v39, v55, v115
	v_rcp_f32_e32 v38, v38
	v_fmac_f32_e32 v39, v63, v105
	v_fmac_f32_e32 v33, v17, v68
	v_fma_f32 v42, v46, v109, v58
	v_mul_f32_e32 v35, v39, v35
	v_fma_f32 v39, v48, v100, v60
	v_fmac_f32_e32 v61, v49, v94
	v_fmac_f32_e32 v33, v25, v71
	v_fmac_f32_e32 v42, v54, v106
	v_fmac_f32_e32 v39, v56, v112
	v_fmac_f32_e32 v61, v57, v95
	v_fmac_f32_e32 v33, v29, v69
	v_mul_f32_e32 v2, v5, v2
	v_add_u32_e32 v1, s34, v1
	v_fmac_f32_e32 v42, v62, v107
	v_fmac_f32_e32 v39, v64, v98
	v_fmac_f32_e32 v61, v65, v96
	v_mul_f32_e32 v37, v37, v38
	v_mul_f32_e32 v5, v33, v2
	v_cvt_pk_bf16_f32 v4, v6, v7
	v_mad_i64_i32 v[6:7], s[36:37], v1, s50, v[66:67]
	v_mul_f32_e32 v34, v42, v34
	v_mul_f32_e32 v36, v39, v36
	v_mul_f32_e32 v10, v61, v37
	v_cvt_pk_bf16_f32 v2, v34, v35
	v_cvt_pk_bf16_f32 v3, v36, v10
	v_cvt_pk_bf16_f32 v5, v9, v5
	global_store_dwordx4 v[6:7], v[2:5], off sc1

.LBB0_1135:
	ds_read_b128 v[172:175], v4
	ds_read_b128 v[176:179], v4 offset:16896
	ds_read_b128 v[180:183], v4 offset:33792
	ds_read_b128 v[184:187], v4 offset:50688
	s_waitcnt lgkmcnt(3)
	v_lshlrev_b32_e32 v188, 16, v172
	v_and_b32_e32 v189, 0xffff0000, v172
	v_lshlrev_b32_e32 v190, 16, v173
	v_and_b32_e32 v191, 0xffff0000, v173
	v_lshlrev_b32_e32 v192, 16, v174
	v_and_b32_e32 v193, 0xffff0000, v174
	v_lshlrev_b32_e32 v194, 16, v175
	v_and_b32_e32 v195, 0xffff0000, v175
	s_waitcnt vmcnt(18)
	v_lshlrev_b32_e32 v196, 16, v26
	v_and_b32_e32 v197, 0xffff0000, v26
	v_lshlrev_b32_e32 v198, 16, v27
	v_and_b32_e32 v199, 0xffff0000, v27
	v_lshlrev_b32_e32 v200, 16, v28
	v_and_b32_e32 v201, 0xffff0000, v28
	v_lshlrev_b32_e32 v202, 16, v29
	v_and_b32_e32 v203, 0xffff0000, v29
	v_fmac_f32_e32 v196, v90, v188
	v_fmac_f32_e32 v197, v91, v189
	v_fmac_f32_e32 v198, v92, v190
	v_fmac_f32_e32 v199, v93, v191
	v_fmac_f32_e32 v200, v94, v192
	v_fmac_f32_e32 v201, v95, v193
	v_fmac_f32_e32 v202, v96, v194
	v_fmac_f32_e32 v203, v97, v195
	v_cvt_pk_bf16_f32 v26, v196, v197
	v_cvt_pk_bf16_f32 v27, v198, v199
	v_cvt_pk_bf16_f32 v28, v200, v201
	v_cvt_pk_bf16_f32 v29, v202, v203
	global_store_dwordx4 v6, v[26:29], s[4:5] sc1
	s_waitcnt lgkmcnt(2)
	v_lshlrev_b32_e32 v188, 16, v176
	v_and_b32_e32 v189, 0xffff0000, v176
	v_lshlrev_b32_e32 v190, 16, v177
	v_and_b32_e32 v191, 0xffff0000, v177
	v_lshlrev_b32_e32 v192, 16, v178
	v_and_b32_e32 v193, 0xffff0000, v178
	v_lshlrev_b32_e32 v194, 16, v179
	v_and_b32_e32 v195, 0xffff0000, v179
	v_lshlrev_b32_e32 v196, 16, v30
	v_and_b32_e32 v197, 0xffff0000, v30
	v_lshlrev_b32_e32 v198, 16, v31
	v_and_b32_e32 v199, 0xffff0000, v31
	v_lshlrev_b32_e32 v200, 16, v32
	v_and_b32_e32 v201, 0xffff0000, v32
	v_lshlrev_b32_e32 v202, 16, v33
	v_and_b32_e32 v203, 0xffff0000, v33
	v_fmac_f32_e32 v196, v90, v188
	v_fmac_f32_e32 v197, v91, v189
	v_fmac_f32_e32 v198, v92, v190
	v_fmac_f32_e32 v199, v93, v191
	v_fmac_f32_e32 v200, v94, v192
	v_fmac_f32_e32 v201, v95, v193
	v_fmac_f32_e32 v202, v96, v194
	v_fmac_f32_e32 v203, v97, v195
	v_cvt_pk_bf16_f32 v30, v196, v197
	v_cvt_pk_bf16_f32 v31, v198, v199
	v_cvt_pk_bf16_f32 v32, v200, v201
	v_cvt_pk_bf16_f32 v33, v202, v203
	global_store_dwordx4 v7, v[30:33], s[4:5] sc1
	s_waitcnt lgkmcnt(1)
	v_lshlrev_b32_e32 v188, 16, v180
	v_and_b32_e32 v189, 0xffff0000, v180
	v_lshlrev_b32_e32 v190, 16, v181
	v_and_b32_e32 v191, 0xffff0000, v181
	v_lshlrev_b32_e32 v192, 16, v182
	v_and_b32_e32 v193, 0xffff0000, v182
	v_lshlrev_b32_e32 v194, 16, v183
	v_and_b32_e32 v195, 0xffff0000, v183
	v_lshlrev_b32_e32 v196, 16, v34
	v_and_b32_e32 v197, 0xffff0000, v34
	v_lshlrev_b32_e32 v198, 16, v35
	v_and_b32_e32 v199, 0xffff0000, v35
	v_lshlrev_b32_e32 v200, 16, v36
	v_and_b32_e32 v201, 0xffff0000, v36
	v_lshlrev_b32_e32 v202, 16, v37
	v_and_b32_e32 v203, 0xffff0000, v37
	v_fmac_f32_e32 v196, v90, v188
	v_fmac_f32_e32 v197, v91, v189
	v_fmac_f32_e32 v198, v92, v190
	v_fmac_f32_e32 v199, v93, v191
	v_fmac_f32_e32 v200, v94, v192
	v_fmac_f32_e32 v201, v95, v193
	v_fmac_f32_e32 v202, v96, v194
	v_fmac_f32_e32 v203, v97, v195
	v_cvt_pk_bf16_f32 v34, v196, v197
	v_cvt_pk_bf16_f32 v35, v198, v199
	v_cvt_pk_bf16_f32 v36, v200, v201
	v_cvt_pk_bf16_f32 v37, v202, v203
	global_store_dwordx4 v8, v[34:37], s[4:5] sc1
	s_waitcnt lgkmcnt(0)
	v_lshlrev_b32_e32 v188, 16, v184
	v_and_b32_e32 v189, 0xffff0000, v184
	v_lshlrev_b32_e32 v190, 16, v185
	v_and_b32_e32 v191, 0xffff0000, v185
	v_lshlrev_b32_e32 v192, 16, v186
	v_and_b32_e32 v193, 0xffff0000, v186
	v_lshlrev_b32_e32 v194, 16, v187
	v_and_b32_e32 v195, 0xffff0000, v187
	ds_read_b128 v[172:175], v4 offset:256
	ds_read_b128 v[176:179], v4 offset:17152
	ds_read_b128 v[180:183], v4 offset:34048
	ds_read_b128 v[184:187], v4 offset:50944
	v_lshlrev_b32_e32 v196, 16, v38
	v_and_b32_e32 v197, 0xffff0000, v38
	v_lshlrev_b32_e32 v198, 16, v39
	v_and_b32_e32 v199, 0xffff0000, v39
	v_lshlrev_b32_e32 v200, 16, v40
	v_and_b32_e32 v201, 0xffff0000, v40
	v_lshlrev_b32_e32 v202, 16, v41
	v_and_b32_e32 v203, 0xffff0000, v41
	v_fmac_f32_e32 v196, v90, v188
	v_fmac_f32_e32 v197, v91, v189
	v_fmac_f32_e32 v198, v92, v190
	v_fmac_f32_e32 v199, v93, v191
	v_fmac_f32_e32 v200, v94, v192
	v_fmac_f32_e32 v201, v95, v193
	v_fmac_f32_e32 v202, v96, v194
	v_fmac_f32_e32 v203, v97, v195
	v_cvt_pk_bf16_f32 v38, v196, v197
	v_cvt_pk_bf16_f32 v39, v198, v199
	v_cvt_pk_bf16_f32 v40, v200, v201
	v_cvt_pk_bf16_f32 v41, v202, v203
	global_store_dwordx4 v9, v[38:41], s[4:5] sc1
	s_waitcnt lgkmcnt(3)
	v_lshlrev_b32_e32 v188, 16, v172
	v_and_b32_e32 v189, 0xffff0000, v172
	v_lshlrev_b32_e32 v190, 16, v173
	v_and_b32_e32 v191, 0xffff0000, v173
	v_lshlrev_b32_e32 v192, 16, v174
	v_and_b32_e32 v193, 0xffff0000, v174
	v_lshlrev_b32_e32 v194, 16, v175
	v_and_b32_e32 v195, 0xffff0000, v175
	s_waitcnt vmcnt(16)
	v_lshlrev_b32_e32 v196, 16, v42
	v_and_b32_e32 v197, 0xffff0000, v42
	v_lshlrev_b32_e32 v198, 16, v43
	v_and_b32_e32 v199, 0xffff0000, v43
	v_lshlrev_b32_e32 v200, 16, v44
	v_and_b32_e32 v201, 0xffff0000, v44
	v_lshlrev_b32_e32 v202, 16, v45
	v_and_b32_e32 v203, 0xffff0000, v45
	v_fmac_f32_e32 v196, v98, v188
	v_fmac_f32_e32 v197, v99, v189
	v_fmac_f32_e32 v198, v100, v190
	v_fmac_f32_e32 v199, v101, v191
	v_fmac_f32_e32 v200, v102, v192
	v_fmac_f32_e32 v201, v103, v193
	v_fmac_f32_e32 v202, v104, v194
	v_fmac_f32_e32 v203, v105, v195
	v_cvt_pk_bf16_f32 v42, v196, v197
	v_cvt_pk_bf16_f32 v43, v198, v199
	v_cvt_pk_bf16_f32 v44, v200, v201
	v_cvt_pk_bf16_f32 v45, v202, v203
	global_store_dwordx4 v10, v[42:45], s[4:5] sc1
	s_waitcnt lgkmcnt(2)
	v_lshlrev_b32_e32 v188, 16, v176
	v_and_b32_e32 v189, 0xffff0000, v176
	v_lshlrev_b32_e32 v190, 16, v177
	v_and_b32_e32 v191, 0xffff0000, v177
	v_lshlrev_b32_e32 v192, 16, v178
	v_and_b32_e32 v193, 0xffff0000, v178
	v_lshlrev_b32_e32 v194, 16, v179
	v_and_b32_e32 v195, 0xffff0000, v179
	v_lshlrev_b32_e32 v196, 16, v46
	v_and_b32_e32 v197, 0xffff0000, v46
	v_lshlrev_b32_e32 v198, 16, v47
	v_and_b32_e32 v199, 0xffff0000, v47
	v_lshlrev_b32_e32 v200, 16, v48
	v_and_b32_e32 v201, 0xffff0000, v48
	v_lshlrev_b32_e32 v202, 16, v49
	v_and_b32_e32 v203, 0xffff0000, v49
	v_fmac_f32_e32 v196, v98, v188
	v_fmac_f32_e32 v197, v99, v189
	v_fmac_f32_e32 v198, v100, v190
	v_fmac_f32_e32 v199, v101, v191
	v_fmac_f32_e32 v200, v102, v192
	v_fmac_f32_e32 v201, v103, v193
	v_fmac_f32_e32 v202, v104, v194
	v_fmac_f32_e32 v203, v105, v195
	v_cvt_pk_bf16_f32 v46, v196, v197
	v_cvt_pk_bf16_f32 v47, v198, v199
	v_cvt_pk_bf16_f32 v48, v200, v201
	v_cvt_pk_bf16_f32 v49, v202, v203
	global_store_dwordx4 v11, v[46:49], s[4:5] sc1
	s_waitcnt lgkmcnt(1)
	v_lshlrev_b32_e32 v188, 16, v180
	v_and_b32_e32 v189, 0xffff0000, v180
	v_lshlrev_b32_e32 v190, 16, v181
	v_and_b32_e32 v191, 0xffff0000, v181
	v_lshlrev_b32_e32 v192, 16, v182
	v_and_b32_e32 v193, 0xffff0000, v182
	v_lshlrev_b32_e32 v194, 16, v183
	v_and_b32_e32 v195, 0xffff0000, v183
	v_lshlrev_b32_e32 v196, 16, v50
	v_and_b32_e32 v197, 0xffff0000, v50
	v_lshlrev_b32_e32 v198, 16, v51
	v_and_b32_e32 v199, 0xffff0000, v51
	v_lshlrev_b32_e32 v200, 16, v52
	v_and_b32_e32 v201, 0xffff0000, v52
	v_lshlrev_b32_e32 v202, 16, v53
	v_and_b32_e32 v203, 0xffff0000, v53
	v_fmac_f32_e32 v196, v98, v188
	v_fmac_f32_e32 v197, v99, v189
	v_fmac_f32_e32 v198, v100, v190
	v_fmac_f32_e32 v199, v101, v191
	v_fmac_f32_e32 v200, v102, v192
	v_fmac_f32_e32 v201, v103, v193
	v_fmac_f32_e32 v202, v104, v194
	v_fmac_f32_e32 v203, v105, v195
	v_cvt_pk_bf16_f32 v50, v196, v197
	v_cvt_pk_bf16_f32 v51, v198, v199
	v_cvt_pk_bf16_f32 v52, v200, v201
	v_cvt_pk_bf16_f32 v53, v202, v203
	global_store_dwordx4 v12, v[50:53], s[4:5] sc1
	s_waitcnt lgkmcnt(0)
	v_lshlrev_b32_e32 v188, 16, v184
	v_and_b32_e32 v189, 0xffff0000, v184
	v_lshlrev_b32_e32 v190, 16, v185
	v_and_b32_e32 v191, 0xffff0000, v185
	v_lshlrev_b32_e32 v192, 16, v186
	v_and_b32_e32 v193, 0xffff0000, v186
	v_lshlrev_b32_e32 v194, 16, v187
	v_and_b32_e32 v195, 0xffff0000, v187
	ds_read_b128 v[172:175], v5
	ds_read_b128 v[176:179], v5 offset:16896
	ds_read_b128 v[180:183], v5 offset:33792
	ds_read_b128 v[184:187], v5 offset:50688
	v_lshlrev_b32_e32 v196, 16, v54
	v_and_b32_e32 v197, 0xffff0000, v54
	v_lshlrev_b32_e32 v198, 16, v55
	v_and_b32_e32 v199, 0xffff0000, v55
	v_lshlrev_b32_e32 v200, 16, v56
	v_and_b32_e32 v201, 0xffff0000, v56
	v_lshlrev_b32_e32 v202, 16, v57
	v_and_b32_e32 v203, 0xffff0000, v57
	v_fmac_f32_e32 v196, v98, v188
	v_fmac_f32_e32 v197, v99, v189
	v_fmac_f32_e32 v198, v100, v190
	v_fmac_f32_e32 v199, v101, v191
	v_fmac_f32_e32 v200, v102, v192
	v_fmac_f32_e32 v201, v103, v193
	v_fmac_f32_e32 v202, v104, v194
	v_fmac_f32_e32 v203, v105, v195
	v_cvt_pk_bf16_f32 v54, v196, v197
	v_cvt_pk_bf16_f32 v55, v198, v199
	v_cvt_pk_bf16_f32 v56, v200, v201
	v_cvt_pk_bf16_f32 v57, v202, v203
	global_store_dwordx4 v13, v[54:57], s[4:5] sc1
	s_waitcnt lgkmcnt(3)
	v_lshlrev_b32_e32 v188, 16, v172
	v_and_b32_e32 v189, 0xffff0000, v172
	v_lshlrev_b32_e32 v190, 16, v173
	v_and_b32_e32 v191, 0xffff0000, v173
	v_lshlrev_b32_e32 v192, 16, v174
	v_and_b32_e32 v193, 0xffff0000, v174
	v_lshlrev_b32_e32 v194, 16, v175
	v_and_b32_e32 v195, 0xffff0000, v175
	s_waitcnt vmcnt(14)
	v_lshlrev_b32_e32 v196, 16, v58
	v_and_b32_e32 v197, 0xffff0000, v58
	v_lshlrev_b32_e32 v198, 16, v59
	v_and_b32_e32 v199, 0xffff0000, v59
	v_lshlrev_b32_e32 v200, 16, v60
	v_and_b32_e32 v201, 0xffff0000, v60
	v_lshlrev_b32_e32 v202, 16, v61
	v_and_b32_e32 v203, 0xffff0000, v61
	v_fmac_f32_e32 v196, v106, v188
	v_fmac_f32_e32 v197, v107, v189
	v_fmac_f32_e32 v198, v108, v190
	v_fmac_f32_e32 v199, v109, v191
	v_fmac_f32_e32 v200, v110, v192
	v_fmac_f32_e32 v201, v111, v193
	v_fmac_f32_e32 v202, v112, v194
	v_fmac_f32_e32 v203, v113, v195
	v_cvt_pk_bf16_f32 v58, v196, v197
	v_cvt_pk_bf16_f32 v59, v198, v199
	v_cvt_pk_bf16_f32 v60, v200, v201
	v_cvt_pk_bf16_f32 v61, v202, v203
	global_store_dwordx4 v14, v[58:61], s[4:5] sc1
	s_waitcnt lgkmcnt(2)
	v_lshlrev_b32_e32 v188, 16, v176
	v_and_b32_e32 v189, 0xffff0000, v176
	v_lshlrev_b32_e32 v190, 16, v177
	v_and_b32_e32 v191, 0xffff0000, v177
	v_lshlrev_b32_e32 v192, 16, v178
	v_and_b32_e32 v193, 0xffff0000, v178
	v_lshlrev_b32_e32 v194, 16, v179
	v_and_b32_e32 v195, 0xffff0000, v179
	v_lshlrev_b32_e32 v196, 16, v62
	v_and_b32_e32 v197, 0xffff0000, v62
	v_lshlrev_b32_e32 v198, 16, v63
	v_and_b32_e32 v199, 0xffff0000, v63
	v_lshlrev_b32_e32 v200, 16, v64
	v_and_b32_e32 v201, 0xffff0000, v64
	v_lshlrev_b32_e32 v202, 16, v65
	v_and_b32_e32 v203, 0xffff0000, v65
	v_fmac_f32_e32 v196, v106, v188
	v_fmac_f32_e32 v197, v107, v189
	v_fmac_f32_e32 v198, v108, v190
	v_fmac_f32_e32 v199, v109, v191
	v_fmac_f32_e32 v200, v110, v192
	v_fmac_f32_e32 v201, v111, v193
	v_fmac_f32_e32 v202, v112, v194
	v_fmac_f32_e32 v203, v113, v195
	v_cvt_pk_bf16_f32 v62, v196, v197
	v_cvt_pk_bf16_f32 v63, v198, v199
	v_cvt_pk_bf16_f32 v64, v200, v201
	v_cvt_pk_bf16_f32 v65, v202, v203
	global_store_dwordx4 v15, v[62:65], s[4:5] sc1
	s_waitcnt lgkmcnt(1)
	v_lshlrev_b32_e32 v188, 16, v180
	v_and_b32_e32 v189, 0xffff0000, v180
	v_lshlrev_b32_e32 v190, 16, v181
	v_and_b32_e32 v191, 0xffff0000, v181
	v_lshlrev_b32_e32 v192, 16, v182
	v_and_b32_e32 v193, 0xffff0000, v182
	v_lshlrev_b32_e32 v194, 16, v183
	v_and_b32_e32 v195, 0xffff0000, v183
	v_lshlrev_b32_e32 v196, 16, v66
	v_and_b32_e32 v197, 0xffff0000, v66
	v_lshlrev_b32_e32 v198, 16, v67
	v_and_b32_e32 v199, 0xffff0000, v67
	v_lshlrev_b32_e32 v200, 16, v68
	v_and_b32_e32 v201, 0xffff0000, v68
	v_lshlrev_b32_e32 v202, 16, v69
	v_and_b32_e32 v203, 0xffff0000, v69
	v_fmac_f32_e32 v196, v106, v188
	v_fmac_f32_e32 v197, v107, v189
	v_fmac_f32_e32 v198, v108, v190
	v_fmac_f32_e32 v199, v109, v191
	v_fmac_f32_e32 v200, v110, v192
	v_fmac_f32_e32 v201, v111, v193
	v_fmac_f32_e32 v202, v112, v194
	v_fmac_f32_e32 v203, v113, v195
	v_cvt_pk_bf16_f32 v66, v196, v197
	v_cvt_pk_bf16_f32 v67, v198, v199
	v_cvt_pk_bf16_f32 v68, v200, v201
	v_cvt_pk_bf16_f32 v69, v202, v203
	global_store_dwordx4 v16, v[66:69], s[4:5] sc1
	s_waitcnt lgkmcnt(0)
	v_lshlrev_b32_e32 v188, 16, v184
	v_and_b32_e32 v189, 0xffff0000, v184
	v_lshlrev_b32_e32 v190, 16, v185
	v_and_b32_e32 v191, 0xffff0000, v185
	v_lshlrev_b32_e32 v192, 16, v186
	v_and_b32_e32 v193, 0xffff0000, v186
	v_lshlrev_b32_e32 v194, 16, v187
	v_and_b32_e32 v195, 0xffff0000, v187
	ds_read_b128 v[172:175], v5 offset:256
	ds_read_b128 v[176:179], v5 offset:17152
	ds_read_b128 v[180:183], v5 offset:34048
	ds_read_b128 v[184:187], v5 offset:50944
	v_lshlrev_b32_e32 v196, 16, v70
	v_and_b32_e32 v197, 0xffff0000, v70
	v_lshlrev_b32_e32 v198, 16, v71
	v_and_b32_e32 v199, 0xffff0000, v71
	v_lshlrev_b32_e32 v200, 16, v72
	v_and_b32_e32 v201, 0xffff0000, v72
	v_lshlrev_b32_e32 v202, 16, v73
	v_and_b32_e32 v203, 0xffff0000, v73
	v_fmac_f32_e32 v196, v106, v188
	v_fmac_f32_e32 v197, v107, v189
	v_fmac_f32_e32 v198, v108, v190
	v_fmac_f32_e32 v199, v109, v191
	v_fmac_f32_e32 v200, v110, v192
	v_fmac_f32_e32 v201, v111, v193
	v_fmac_f32_e32 v202, v112, v194
	v_fmac_f32_e32 v203, v113, v195
	v_cvt_pk_bf16_f32 v70, v196, v197
	v_cvt_pk_bf16_f32 v71, v198, v199
	v_cvt_pk_bf16_f32 v72, v200, v201
	v_cvt_pk_bf16_f32 v73, v202, v203
	global_store_dwordx4 v17, v[70:73], s[4:5] sc1
	s_waitcnt lgkmcnt(3)
	v_lshlrev_b32_e32 v188, 16, v172
	v_and_b32_e32 v189, 0xffff0000, v172
	v_lshlrev_b32_e32 v190, 16, v173
	v_and_b32_e32 v191, 0xffff0000, v173
	v_lshlrev_b32_e32 v192, 16, v174
	v_and_b32_e32 v193, 0xffff0000, v174
	v_lshlrev_b32_e32 v194, 16, v175
	v_and_b32_e32 v195, 0xffff0000, v175
	s_waitcnt vmcnt(12)
	v_lshlrev_b32_e32 v196, 16, v74
	v_and_b32_e32 v197, 0xffff0000, v74
	v_lshlrev_b32_e32 v198, 16, v75
	v_and_b32_e32 v199, 0xffff0000, v75
	v_lshlrev_b32_e32 v200, 16, v76
	v_and_b32_e32 v201, 0xffff0000, v76
	v_lshlrev_b32_e32 v202, 16, v77
	v_and_b32_e32 v203, 0xffff0000, v77
	v_fmac_f32_e32 v196, v114, v188
	v_fmac_f32_e32 v197, v115, v189
	v_fmac_f32_e32 v198, v116, v190
	v_fmac_f32_e32 v199, v117, v191
	v_fmac_f32_e32 v200, v118, v192
	v_fmac_f32_e32 v201, v119, v193
	v_fmac_f32_e32 v202, v120, v194
	v_fmac_f32_e32 v203, v121, v195
	v_cvt_pk_bf16_f32 v74, v196, v197
	v_cvt_pk_bf16_f32 v75, v198, v199
	v_cvt_pk_bf16_f32 v76, v200, v201
	v_cvt_pk_bf16_f32 v77, v202, v203
	global_store_dwordx4 v18, v[74:77], s[4:5] sc1
	s_waitcnt lgkmcnt(2)
	v_lshlrev_b32_e32 v188, 16, v176
	v_and_b32_e32 v189, 0xffff0000, v176
	v_lshlrev_b32_e32 v190, 16, v177
	v_and_b32_e32 v191, 0xffff0000, v177
	v_lshlrev_b32_e32 v192, 16, v178
	v_and_b32_e32 v193, 0xffff0000, v178
	v_lshlrev_b32_e32 v194, 16, v179
	v_and_b32_e32 v195, 0xffff0000, v179
	v_lshlrev_b32_e32 v196, 16, v78
	v_and_b32_e32 v197, 0xffff0000, v78
	v_lshlrev_b32_e32 v198, 16, v79
	v_and_b32_e32 v199, 0xffff0000, v79
	v_lshlrev_b32_e32 v200, 16, v80
	v_and_b32_e32 v201, 0xffff0000, v80
	v_lshlrev_b32_e32 v202, 16, v81
	v_and_b32_e32 v203, 0xffff0000, v81
	v_fmac_f32_e32 v196, v114, v188
	v_fmac_f32_e32 v197, v115, v189
	v_fmac_f32_e32 v198, v116, v190
	v_fmac_f32_e32 v199, v117, v191
	v_fmac_f32_e32 v200, v118, v192
	v_fmac_f32_e32 v201, v119, v193
	v_fmac_f32_e32 v202, v120, v194
	v_fmac_f32_e32 v203, v121, v195
	v_cvt_pk_bf16_f32 v78, v196, v197
	v_cvt_pk_bf16_f32 v79, v198, v199
	v_cvt_pk_bf16_f32 v80, v200, v201
	v_cvt_pk_bf16_f32 v81, v202, v203
	global_store_dwordx4 v19, v[78:81], s[4:5] sc1
	s_waitcnt lgkmcnt(1)
	v_lshlrev_b32_e32 v188, 16, v180
	v_and_b32_e32 v189, 0xffff0000, v180
	v_lshlrev_b32_e32 v190, 16, v181
	v_and_b32_e32 v191, 0xffff0000, v181
	v_lshlrev_b32_e32 v192, 16, v182
	v_and_b32_e32 v193, 0xffff0000, v182
	v_lshlrev_b32_e32 v194, 16, v183
	v_and_b32_e32 v195, 0xffff0000, v183
	v_lshlrev_b32_e32 v196, 16, v82
	v_and_b32_e32 v197, 0xffff0000, v82
	v_lshlrev_b32_e32 v198, 16, v83
	v_and_b32_e32 v199, 0xffff0000, v83
	v_lshlrev_b32_e32 v200, 16, v84
	v_and_b32_e32 v201, 0xffff0000, v84
	v_lshlrev_b32_e32 v202, 16, v85
	v_and_b32_e32 v203, 0xffff0000, v85
	v_fmac_f32_e32 v196, v114, v188
	v_fmac_f32_e32 v197, v115, v189
	v_fmac_f32_e32 v198, v116, v190
	v_fmac_f32_e32 v199, v117, v191
	v_fmac_f32_e32 v200, v118, v192
	v_fmac_f32_e32 v201, v119, v193
	v_fmac_f32_e32 v202, v120, v194
	v_fmac_f32_e32 v203, v121, v195
	v_cvt_pk_bf16_f32 v82, v196, v197
	v_cvt_pk_bf16_f32 v83, v198, v199
	v_cvt_pk_bf16_f32 v84, v200, v201
	v_cvt_pk_bf16_f32 v85, v202, v203
	global_store_dwordx4 v20, v[82:85], s[4:5] sc1
	s_waitcnt lgkmcnt(0)
	v_lshlrev_b32_e32 v188, 16, v184
	v_and_b32_e32 v189, 0xffff0000, v184
	v_lshlrev_b32_e32 v190, 16, v185
	v_and_b32_e32 v191, 0xffff0000, v185
	v_lshlrev_b32_e32 v192, 16, v186
	v_and_b32_e32 v193, 0xffff0000, v186
	v_lshlrev_b32_e32 v194, 16, v187
	v_and_b32_e32 v195, 0xffff0000, v187
	v_lshlrev_b32_e32 v196, 16, v86
	v_and_b32_e32 v197, 0xffff0000, v86
	v_lshlrev_b32_e32 v198, 16, v87
	v_and_b32_e32 v199, 0xffff0000, v87
	v_lshlrev_b32_e32 v200, 16, v88
	v_and_b32_e32 v201, 0xffff0000, v88
	v_lshlrev_b32_e32 v202, 16, v89
	v_and_b32_e32 v203, 0xffff0000, v89
	v_fmac_f32_e32 v196, v114, v188
	v_fmac_f32_e32 v197, v115, v189
	v_fmac_f32_e32 v198, v116, v190
	v_fmac_f32_e32 v199, v117, v191
	v_fmac_f32_e32 v200, v118, v192
	v_fmac_f32_e32 v201, v119, v193
	v_fmac_f32_e32 v202, v120, v194
	v_fmac_f32_e32 v203, v121, v195
	v_cvt_pk_bf16_f32 v86, v196, v197
	v_cvt_pk_bf16_f32 v87, v198, v199
	v_cvt_pk_bf16_f32 v88, v200, v201
	v_cvt_pk_bf16_f32 v89, v202, v203
	global_store_dwordx4 v21, v[86:89], s[4:5] sc1
	s_mov_b64 s[6:7], 0
	s_barrier
	s_branch .LBB0_1097

.LBB0_1798:
	s_or_b64 exec, exec, s[4:5]
	s_and_b32 s36, s35, 3
	s_cmp_eq_u32 s36, 0
	s_cselect_b64 s[6:7], -1, 0
	s_cmp_lt_i32 s35, 32
	v_cmp_ne_u32_e32 vcc, 0, v83
	s_cselect_b64 s[4:5], -1, 0
	s_or_b64 s[6:7], s[6:7], vcc
	s_waitcnt lgkmcnt(1)
	v_lshlrev_b32_e32 v77, 16, v70
	v_and_b32_e32 v78, 0xffff0000, v70
	v_lshlrev_b32_e32 v75, 16, v71
	v_and_b32_e32 v76, 0xffff0000, v71
	v_lshlrev_b32_e32 v71, 16, v72
	v_and_b32_e32 v72, 0xffff0000, v72
	v_lshlrev_b32_e32 v1, 16, v73
	v_and_b32_e32 v70, 0xffff0000, v73
	s_nor_b64 s[6:7], s[4:5], s[6:7]
	s_and_saveexec_b64 s[38:39], s[6:7]
	s_xor_b64 s[6:7], exec, s[38:39]
	s_or_saveexec_b64 s[6:7], s[6:7]
	s_waitcnt lgkmcnt(0)
	v_lshlrev_b32_e32 v118, 16, v66
	v_and_b32_e32 v115, 0xffff0000, v66
	v_lshlrev_b32_e32 v112, 16, v67
	v_and_b32_e32 v110, 0xffff0000, v67
	v_lshlrev_b32_e32 v108, 16, v68
	v_and_b32_e32 v104, 0xffff0000, v68
	v_lshlrev_b32_e32 v102, 16, v69
	v_and_b32_e32 v100, 0xffff0000, v69
	s_lshl_b32 s34, s35, 8
	v_lshl_add_u64 v[66:67], v[80:81], 1, s[12:13]
	s_xor_b64 exec, exec, s[6:7]
	s_cbranch_execz .LBB0_1802
	s_waitcnt vmcnt(8)
	v_fma_f32 v68, v38, v122, v34
	v_fmac_f32_e32 v68, v42, v77
	v_fmac_f32_e32 v68, v50, v99
	v_mul_f32_e32 v69, 0xbfb8aa3b, v68
	v_exp_f32_e32 v69, v69
	v_fma_f32 v80, v39, v120, v35
	v_fmac_f32_e32 v80, v43, v78
	v_fmac_f32_e32 v80, v51, v98
	v_add_f32_e32 v69, 1.0, v69
	v_mul_f32_e32 v81, 0xbfb8aa3b, v80
	v_rcp_f32_e32 v69, v69
	v_exp_f32_e32 v81, v81
	s_waitcnt vmcnt(1)
	v_fma_f32 v73, v46, v123, v58
	v_fmac_f32_e32 v73, v54, v118
	v_mul_f32_e32 v68, v68, v69
	v_add_f32_e32 v69, 1.0, v81
	v_rcp_f32_e32 v69, v69
	v_fma_f32 v114, v41, v114, v37
	v_fmac_f32_e32 v73, v62, v89
	v_fmac_f32_e32 v114, v45, v76
	v_mul_f32_e32 v69, v80, v69
	v_fma_f32 v80, v40, v117, v36
	v_fmac_f32_e32 v80, v44, v75
	v_fmac_f32_e32 v80, v52, v96
	v_mul_f32_e32 v81, 0xbfb8aa3b, v80
	v_exp_f32_e32 v81, v81
	v_mul_f32_e32 v68, v73, v68
	v_fma_f32 v73, v47, v121, v59
	v_fmac_f32_e32 v114, v53, v94
	v_add_f32_e32 v81, 1.0, v81
	v_fmac_f32_e32 v73, v55, v115
	v_rcp_f32_e32 v81, v81
	v_mul_f32_e32 v117, 0xbfb8aa3b, v114
	v_fmac_f32_e32 v73, v63, v97
	v_exp_f32_e32 v117, v117
	v_mul_f32_e32 v69, v73, v69
	v_fma_f32 v73, v48, v119, v60
	v_fmac_f32_e32 v73, v56, v112
	v_fmac_f32_e32 v73, v64, v95
	v_mul_f32_e32 v80, v80, v81
	v_mul_f32_e32 v73, v73, v80
	v_add_f32_e32 v80, 1.0, v117
	v_rcp_f32_e32 v80, v80
	v_fma_f32 v111, v6, v111, v2
	v_fmac_f32_e32 v111, v10, v71
	v_fmac_f32_e32 v111, v18, v92
	v_mul_f32_e32 v80, v114, v80
	v_mul_f32_e32 v114, 0xbfb8aa3b, v111
	v_exp_f32_e32 v114, v114
	v_fma_f32 v81, v49, v116, v61
	v_fmac_f32_e32 v81, v57, v110
	v_fma_f32 v107, v7, v107, v3
	v_fmac_f32_e32 v81, v65, v93
	v_fmac_f32_e32 v107, v11, v72
	v_mul_f32_e32 v80, v81, v80
	s_waitcnt vmcnt(0)
	v_fma_f32 v81, v14, v113, v30
	v_add_f32_e32 v113, 1.0, v114
	v_fmac_f32_e32 v107, v19, v90
	v_rcp_f32_e32 v113, v113
	v_mul_f32_e32 v114, 0xbfb8aa3b, v107
	v_exp_f32_e32 v114, v114
	v_fmac_f32_e32 v81, v22, v108
	v_fmac_f32_e32 v81, v26, v91
	v_mul_f32_e32 v111, v111, v113
	v_mul_f32_e32 v81, v81, v111
	v_add_f32_e32 v111, 1.0, v114
	v_rcp_f32_e32 v111, v111
	v_fma_f32 v105, v8, v105, v4
	v_fmac_f32_e32 v105, v12, v1
	v_fmac_f32_e32 v105, v20, v87
	v_mul_f32_e32 v107, v107, v111
	v_mul_f32_e32 v111, 0xbfb8aa3b, v105
	v_exp_f32_e32 v111, v111
	v_fma_f32 v109, v15, v109, v31
	v_fmac_f32_e32 v109, v23, v104
	v_fma_f32 v101, v9, v101, v5
	v_fmac_f32_e32 v109, v27, v88
	v_fmac_f32_e32 v101, v13, v70
	v_mul_f32_e32 v107, v109, v107
	v_add_f32_e32 v109, 1.0, v111
	v_fmac_f32_e32 v101, v21, v85
	v_rcp_f32_e32 v109, v109
	v_mul_f32_e32 v111, 0xbfb8aa3b, v101
	v_exp_f32_e32 v111, v111
	v_fma_f32 v106, v16, v106, v32
	v_fmac_f32_e32 v106, v24, v102
	v_fmac_f32_e32 v106, v28, v86
	v_mul_f32_e32 v105, v105, v109
	v_mul_f32_e32 v105, v106, v105
	v_add_f32_e32 v106, 1.0, v111
	v_rcp_f32_e32 v106, v106
	v_fma_f32 v103, v17, v103, v33
	v_fmac_f32_e32 v103, v25, v100
	v_cvt_pk_bf16_f32 v120, v68, v69
	v_add_u32_e32 v68, s34, v83
	v_fmac_f32_e32 v103, v29, v84
	v_mul_f32_e32 v101, v101, v106
	v_mad_i64_i32 v[68:69], s[38:39], v68, s50, v[66:67]
	v_mul_f32_e32 v101, v103, v101
	v_cvt_pk_bf16_f32 v121, v73, v80
	v_cvt_pk_bf16_f32 v122, v81, v107
	v_cvt_pk_bf16_f32 v123, v105, v101
	global_store_dwordx4 v[68:69], v[120:123], off sc1

.LBB0_1804:
	s_or_b64 exec, exec, s[6:7]
	s_waitcnt vmcnt(8)
	v_fma_f32 v77, v38, v77, v34
	v_fmac_f32_e32 v77, v42, v99
	v_fmac_f32_e32 v77, v50, v128
	v_mul_f32_e32 v113, 0xbfb8aa3b, v77
	v_exp_f32_e32 v113, v113
	v_fma_f32 v78, v39, v78, v35
	v_fmac_f32_e32 v78, v43, v98
	v_fmac_f32_e32 v78, v51, v123
	s_waitcnt vmcnt(1)
	v_fma_f32 v116, v46, v118, v58
	v_add_f32_e32 v113, 1.0, v113
	v_mul_f32_e32 v118, 0xbfb8aa3b, v78
	v_rcp_f32_e32 v113, v113
	v_exp_f32_e32 v118, v118
	v_fma_f32 v75, v40, v75, v36
	v_fmac_f32_e32 v75, v44, v96
	v_mul_f32_e32 v77, v77, v113
	v_add_f32_e32 v113, 1.0, v118
	v_rcp_f32_e32 v113, v113
	v_fmac_f32_e32 v75, v52, v117
	v_fma_f32 v115, v47, v115, v59
	v_fma_f32 v76, v41, v76, v37
	v_mul_f32_e32 v78, v78, v113
	v_mul_f32_e32 v113, 0xbfb8aa3b, v75
	v_exp_f32_e32 v113, v113
	v_fmac_f32_e32 v115, v55, v97
	v_fmac_f32_e32 v76, v45, v94
	v_fmac_f32_e32 v115, v63, v120
	v_add_f32_e32 v113, 1.0, v113
	v_fmac_f32_e32 v76, v53, v111
	v_mul_f32_e32 v78, v115, v78
	v_rcp_f32_e32 v113, v113
	v_mul_f32_e32 v115, 0xbfb8aa3b, v76
	v_exp_f32_e32 v115, v115
	v_fma_f32 v112, v48, v112, v60
	v_fmac_f32_e32 v112, v56, v95
	v_fmac_f32_e32 v112, v64, v114
	v_mul_f32_e32 v75, v75, v113
	v_mul_f32_e32 v75, v112, v75
	v_add_f32_e32 v112, 1.0, v115
	v_rcp_f32_e32 v112, v112
	v_fma_f32 v71, v6, v71, v2
	v_fmac_f32_e32 v71, v10, v92
	v_fmac_f32_e32 v71, v18, v107
	v_mul_f32_e32 v76, v76, v112
	v_mul_f32_e32 v112, 0xbfb8aa3b, v71
	v_exp_f32_e32 v112, v112
	v_fma_f32 v110, v49, v110, v61
	v_fmac_f32_e32 v110, v57, v93
	v_fma_f32 v72, v7, v72, v3
	v_fmac_f32_e32 v110, v65, v109
	v_fmac_f32_e32 v72, v11, v90
	v_mul_f32_e32 v76, v110, v76
	v_add_f32_e32 v110, 1.0, v112
	v_fmac_f32_e32 v72, v19, v103
	v_rcp_f32_e32 v110, v110
	v_mul_f32_e32 v112, 0xbfb8aa3b, v72
	v_exp_f32_e32 v112, v112
	s_waitcnt vmcnt(0)
	v_fma_f32 v108, v14, v108, v30
	v_fmac_f32_e32 v108, v22, v91
	v_fmac_f32_e32 v108, v26, v105
	v_mul_f32_e32 v71, v71, v110
	v_mul_f32_e32 v71, v108, v71
	v_add_f32_e32 v108, 1.0, v112
	v_rcp_f32_e32 v108, v108
	v_fma_f32 v1, v8, v1, v4
	v_fmac_f32_e32 v1, v12, v87
	v_fmac_f32_e32 v1, v20, v81
	v_mul_f32_e32 v72, v72, v108
	v_mul_f32_e32 v108, 0xbfb8aa3b, v1
	v_exp_f32_e32 v108, v108
	v_fma_f32 v104, v15, v104, v31
	v_fmac_f32_e32 v104, v23, v88
	v_fma_f32 v70, v9, v70, v5
	v_fmac_f32_e32 v104, v27, v101
	v_fmac_f32_e32 v70, v13, v85
	v_mul_f32_e32 v72, v104, v72
	v_add_f32_e32 v104, 1.0, v108
	v_fmac_f32_e32 v70, v21, v73
	v_rcp_f32_e32 v104, v104
	v_mul_f32_e32 v108, 0xbfb8aa3b, v70
	v_exp_f32_e32 v108, v108
	v_fma_f32 v102, v16, v102, v32
	v_fmac_f32_e32 v102, v24, v86
	v_fmac_f32_e32 v102, v28, v80
	v_mul_f32_e32 v1, v1, v104
	v_mul_f32_e32 v1, v102, v1
	v_add_f32_e32 v102, 1.0, v108
	v_rcp_f32_e32 v102, v102
	v_fma_f32 v100, v17, v100, v33
	v_fmac_f32_e32 v100, v25, v84
	v_fmac_f32_e32 v100, v29, v69
	v_mul_f32_e32 v70, v70, v102
	v_fmac_f32_e32 v116, v54, v89
	v_mul_f32_e32 v70, v100, v70
	v_cvt_pk_bf16_f32 v153, v1, v70
	v_add_u32_e32 v1, s34, v106
	v_fmac_f32_e32 v116, v62, v126
	v_cvt_pk_bf16_f32 v152, v71, v72
	v_mad_i64_i32 v[70:71], s[6:7], v1, s50, v[66:67]
	v_or_b32_e32 v1, 2, v83
	v_mul_f32_e32 v77, v116, v77
	v_cvt_pk_bf16_f32 v150, v77, v78
	v_cvt_pk_bf16_f32 v151, v75, v76
	global_store_dwordx4 v[70:71], v[150:153], off sc1
	v_cmp_gt_i32_e32 vcc, s46, v1
	v_mov_b32_e32 v121, 0
	v_mov_b32_e32 v115, 0
	v_mov_b32_e32 v110, 0
	v_mov_b32_e32 v106, 0
	v_mov_b32_e32 v102, 0
	v_mov_b32_e32 v76, 0
	v_mov_b32_e32 v70, 0
	v_mov_b32_e32 v129, 0
	v_mov_b32_e32 v124, 0
	v_mov_b32_e32 v118, 0
	v_mov_b32_e32 v112, 0
	v_mov_b32_e32 v108, 0
	v_mov_b32_e32 v104, 0
	v_mov_b32_e32 v100, 0
	v_mov_b32_e32 v72, 0
	s_and_saveexec_b64 s[6:7], vcc
	s_cbranch_execz .LBB0_1806
	v_mul_lo_u32 v68, v1, s51
	v_add3_u32 v68, 0, v68, v79
	ds_read_b128 v[150:153], v68 offset:528
	ds_read_b128 v[162:165], v68 offset:656
	s_waitcnt lgkmcnt(1)
	v_lshlrev_b32_e32 v129, 16, v150
	v_and_b32_e32 v124, 0xffff0000, v150
	v_lshlrev_b32_e32 v118, 16, v151
	v_and_b32_e32 v112, 0xffff0000, v151
	v_lshlrev_b32_e32 v108, 16, v152
	v_and_b32_e32 v104, 0xffff0000, v152
	v_lshlrev_b32_e32 v100, 16, v153
	v_and_b32_e32 v72, 0xffff0000, v153
	s_waitcnt lgkmcnt(0)
	v_lshlrev_b32_e32 v68, 16, v162
	v_and_b32_e32 v121, 0xffff0000, v162
	v_lshlrev_b32_e32 v115, 16, v163
	v_and_b32_e32 v110, 0xffff0000, v163
	v_lshlrev_b32_e32 v106, 16, v164
	v_and_b32_e32 v102, 0xffff0000, v164
	v_lshlrev_b32_e32 v76, 16, v165
	v_and_b32_e32 v70, 0xffff0000, v165
.LBB0_1806:
	s_or_b64 exec, exec, s[6:7]
	v_fma_f32 v71, v38, v99, v34
	v_fmac_f32_e32 v71, v42, v128
	v_fmac_f32_e32 v71, v50, v129
	v_mul_f32_e32 v75, 0xbfb8aa3b, v71
	v_exp_f32_e32 v75, v75
	v_fma_f32 v78, v39, v98, v35
	v_fmac_f32_e32 v78, v43, v123
	v_fmac_f32_e32 v78, v51, v124
	v_fma_f32 v77, v46, v89, v58
	v_add_f32_e32 v75, 1.0, v75
	v_mul_f32_e32 v89, 0xbfb8aa3b, v78
	v_rcp_f32_e32 v75, v75
	v_exp_f32_e32 v89, v89
	v_fmac_f32_e32 v77, v54, v126
	v_fmac_f32_e32 v77, v62, v68
	v_mul_f32_e32 v71, v71, v75
	v_add_f32_e32 v75, 1.0, v89
	v_rcp_f32_e32 v75, v75
	v_mul_f32_e32 v71, v77, v71
	v_fma_f32 v77, v47, v97, v59
	v_fma_f32 v94, v41, v94, v37
	v_mul_f32_e32 v75, v78, v75
	v_fma_f32 v78, v40, v96, v36
	v_fmac_f32_e32 v78, v44, v117
	v_fmac_f32_e32 v78, v52, v118
	v_mul_f32_e32 v89, 0xbfb8aa3b, v78
	v_exp_f32_e32 v89, v89
	v_fmac_f32_e32 v77, v55, v120
	v_fmac_f32_e32 v94, v45, v111
	v_fmac_f32_e32 v77, v63, v121
	v_add_f32_e32 v89, 1.0, v89
	v_fmac_f32_e32 v94, v53, v112
	v_mul_f32_e32 v75, v77, v75
	v_fma_f32 v77, v48, v95, v60
	v_rcp_f32_e32 v89, v89
	v_mul_f32_e32 v95, 0xbfb8aa3b, v94
	v_exp_f32_e32 v95, v95
	v_fmac_f32_e32 v77, v56, v114
	v_fma_f32 v92, v6, v92, v2
	v_fmac_f32_e32 v77, v64, v115
	v_mul_f32_e32 v78, v78, v89
	v_fmac_f32_e32 v92, v10, v107
	v_mul_f32_e32 v77, v77, v78
	v_add_f32_e32 v78, 1.0, v95
	v_fmac_f32_e32 v92, v18, v108
	v_rcp_f32_e32 v78, v78
	v_fma_f32 v89, v49, v93, v61
	v_mul_f32_e32 v93, 0xbfb8aa3b, v92
	v_exp_f32_e32 v93, v93
	v_fmac_f32_e32 v89, v57, v109
	v_fma_f32 v90, v7, v90, v3
	v_fmac_f32_e32 v89, v65, v110
	v_mul_f32_e32 v78, v94, v78
	v_fmac_f32_e32 v90, v11, v103
	v_mul_f32_e32 v78, v89, v78
	v_fma_f32 v89, v14, v91, v30
	v_add_f32_e32 v91, 1.0, v93
	v_fmac_f32_e32 v90, v19, v104
	v_rcp_f32_e32 v91, v91
	v_mul_f32_e32 v93, 0xbfb8aa3b, v90
	v_exp_f32_e32 v93, v93
	v_fmac_f32_e32 v89, v22, v105
	v_fmac_f32_e32 v89, v26, v106
	v_mul_f32_e32 v91, v92, v91
	v_mul_f32_e32 v89, v89, v91
	v_add_f32_e32 v91, 1.0, v93
	v_rcp_f32_e32 v91, v91
	v_fma_f32 v87, v8, v87, v4
	v_fmac_f32_e32 v87, v12, v81
	v_fmac_f32_e32 v87, v20, v100
	v_mul_f32_e32 v90, v90, v91
	v_mul_f32_e32 v91, 0xbfb8aa3b, v87
	v_exp_f32_e32 v91, v91
	v_fma_f32 v88, v15, v88, v31
	v_fmac_f32_e32 v88, v23, v101
	v_fma_f32 v85, v9, v85, v5
	v_fmac_f32_e32 v88, v27, v102
	v_fmac_f32_e32 v85, v13, v73
	v_mul_f32_e32 v88, v88, v90
	v_add_f32_e32 v90, 1.0, v91
	v_fmac_f32_e32 v85, v21, v72
	v_rcp_f32_e32 v90, v90
	v_mul_f32_e32 v91, 0xbfb8aa3b, v85
	v_exp_f32_e32 v91, v91
	v_fma_f32 v86, v16, v86, v32
	v_fmac_f32_e32 v86, v24, v80
	v_fmac_f32_e32 v86, v28, v76
	v_mul_f32_e32 v87, v87, v90
	v_mul_f32_e32 v87, v86, v87
	v_add_f32_e32 v86, 1.0, v91
	v_rcp_f32_e32 v86, v86
	v_fma_f32 v84, v17, v84, v33
	v_fmac_f32_e32 v84, v25, v69
	v_fmac_f32_e32 v84, v29, v70
	v_mul_f32_e32 v85, v85, v86
	v_add_u32_e32 v1, s34, v1
	v_mul_f32_e32 v90, v84, v85
	v_cvt_pk_bf16_f32 v84, v71, v75
	v_cvt_pk_bf16_f32 v85, v77, v78
	v_cvt_pk_bf16_f32 v86, v89, v88
	v_mad_i64_i32 v[88:89], s[6:7], v1, s50, v[66:67]
	v_or_b32_e32 v78, 3, v83
	v_cvt_pk_bf16_f32 v87, v87, v90
	global_store_dwordx4 v[88:89], v[84:87], off sc1
	v_cmp_gt_i32_e32 vcc, s46, v78
	v_mov_b32_e32 v1, 0
	v_mov_b32_e32 v127, 0
	v_mov_b32_e32 v122, 0
	v_mov_b32_e32 v116, 0
	v_mov_b32_e32 v97, 0
	v_mov_b32_e32 v91, 0
	v_mov_b32_e32 v85, 0
	v_mov_b32_e32 v77, 0
	v_mov_b32_e32 v71, 0
	v_mov_b32_e32 v138, 0
	v_mov_b32_e32 v125, 0
	v_mov_b32_e32 v119, 0
	v_mov_b32_e32 v113, 0
	v_mov_b32_e32 v95, 0
	v_mov_b32_e32 v89, 0
	v_mov_b32_e32 v84, 0
	v_mov_b32_e32 v75, 0
	s_and_saveexec_b64 s[6:7], vcc
	s_cbranch_execz .LBB0_1808
	v_mul_lo_u32 v71, v78, s51
	v_add3_u32 v71, 0, v71, v79
	ds_read_b128 v[84:87], v71 offset:528
	ds_read_b128 v[90:93], v71 offset:656
	s_waitcnt lgkmcnt(1)
	v_lshlrev_b32_e32 v138, 16, v84
	v_and_b32_e32 v125, 0xffff0000, v84
	v_lshlrev_b32_e32 v119, 16, v85
	v_and_b32_e32 v113, 0xffff0000, v85
	v_lshlrev_b32_e32 v95, 16, v86
	v_and_b32_e32 v89, 0xffff0000, v86
	v_lshlrev_b32_e32 v84, 16, v87
	v_and_b32_e32 v75, 0xffff0000, v87
	s_waitcnt lgkmcnt(0)
	v_lshlrev_b32_e32 v127, 16, v90
	v_and_b32_e32 v122, 0xffff0000, v90
	v_lshlrev_b32_e32 v116, 16, v91
	v_and_b32_e32 v97, 0xffff0000, v91
	v_lshlrev_b32_e32 v91, 16, v92
	v_and_b32_e32 v85, 0xffff0000, v92
	v_lshlrev_b32_e32 v77, 16, v93
	v_and_b32_e32 v71, 0xffff0000, v93
.LBB0_1808:
	s_or_b64 exec, exec, s[6:7]
	v_fma_f32 v86, v38, v128, v34
	v_fmac_f32_e32 v86, v42, v129
	v_fmac_f32_e32 v86, v50, v138
	v_mul_f32_e32 v87, 0xbfb8aa3b, v86
	v_exp_f32_e32 v87, v87
	v_fma_f32 v90, v39, v123, v35
	v_fmac_f32_e32 v90, v43, v124
	v_fmac_f32_e32 v90, v51, v125
	v_add_f32_e32 v87, 1.0, v87
	v_mul_f32_e32 v92, 0xbfb8aa3b, v90
	v_rcp_f32_e32 v87, v87
	v_exp_f32_e32 v92, v92
	v_fma_f32 v88, v46, v126, v58
	v_fmac_f32_e32 v88, v54, v68
	v_mul_f32_e32 v86, v86, v87
	v_add_f32_e32 v87, 1.0, v92
	v_rcp_f32_e32 v87, v87
	v_fma_f32 v93, v41, v111, v37
	v_fmac_f32_e32 v88, v62, v127
	v_fmac_f32_e32 v93, v45, v112
	v_mul_f32_e32 v87, v90, v87
	v_fma_f32 v90, v40, v117, v36
	v_fmac_f32_e32 v90, v44, v118
	v_fmac_f32_e32 v90, v52, v119
	v_mul_f32_e32 v92, 0xbfb8aa3b, v90
	v_exp_f32_e32 v92, v92
	v_mul_f32_e32 v86, v88, v86
	v_fma_f32 v88, v47, v120, v59
	v_fmac_f32_e32 v93, v53, v113
	v_add_f32_e32 v92, 1.0, v92
	v_fmac_f32_e32 v88, v55, v121
	v_rcp_f32_e32 v92, v92
	v_mul_f32_e32 v94, 0xbfb8aa3b, v93
	v_fmac_f32_e32 v88, v63, v122
	v_exp_f32_e32 v94, v94
	v_mul_f32_e32 v87, v88, v87
	v_fma_f32 v88, v48, v114, v60
	v_fmac_f32_e32 v88, v56, v115
	v_fmac_f32_e32 v88, v64, v116
	v_mul_f32_e32 v90, v90, v92
	v_mul_f32_e32 v88, v88, v90
	v_add_f32_e32 v90, 1.0, v94
	v_rcp_f32_e32 v90, v90
	v_fma_f32 v96, v7, v103, v3
	v_fmac_f32_e32 v96, v11, v104
	v_fma_f32 v92, v49, v109, v61
	v_mul_f32_e32 v90, v93, v90
	v_fma_f32 v93, v6, v107, v2
	v_fmac_f32_e32 v93, v10, v108
	v_fmac_f32_e32 v93, v18, v95
	v_mul_f32_e32 v94, 0xbfb8aa3b, v93
	v_exp_f32_e32 v94, v94
	v_fmac_f32_e32 v96, v19, v89
	v_fmac_f32_e32 v92, v57, v110
	v_mul_f32_e32 v98, 0xbfb8aa3b, v96
	v_add_f32_e32 v94, 1.0, v94
	v_rcp_f32_e32 v94, v94
	v_fmac_f32_e32 v92, v65, v97
	v_exp_f32_e32 v98, v98
	v_mul_f32_e32 v90, v92, v90
	v_fma_f32 v92, v14, v105, v30
	v_fmac_f32_e32 v92, v22, v106
	v_fmac_f32_e32 v92, v26, v91
	v_mul_f32_e32 v93, v93, v94
	v_mul_f32_e32 v92, v92, v93
	v_add_f32_e32 v93, 1.0, v98
	v_rcp_f32_e32 v93, v93
	v_fma_f32 v81, v8, v81, v4
	v_fmac_f32_e32 v81, v12, v100
	v_fmac_f32_e32 v81, v20, v84
	v_mul_f32_e32 v93, v96, v93
	v_mul_f32_e32 v96, 0xbfb8aa3b, v81
	v_exp_f32_e32 v96, v96
	v_fma_f32 v94, v15, v101, v31
	v_fmac_f32_e32 v94, v23, v102
	v_fma_f32 v73, v9, v73, v5
	v_fmac_f32_e32 v94, v27, v85
	v_fmac_f32_e32 v73, v13, v72
	v_mul_f32_e32 v93, v94, v93
	v_add_f32_e32 v94, 1.0, v96
	v_fmac_f32_e32 v73, v21, v75
	v_rcp_f32_e32 v94, v94
	v_mul_f32_e32 v96, 0xbfb8aa3b, v73
	v_exp_f32_e32 v96, v96
	v_fma_f32 v80, v16, v80, v32
	v_fmac_f32_e32 v80, v24, v76
	v_fmac_f32_e32 v80, v28, v77
	v_mul_f32_e32 v81, v81, v94
	v_mul_f32_e32 v80, v80, v81
	v_add_f32_e32 v81, 1.0, v96
	v_rcp_f32_e32 v81, v81
	v_fma_f32 v69, v17, v69, v33
	v_fmac_f32_e32 v69, v25, v70
	v_fmac_f32_e32 v69, v29, v71
	v_mul_f32_e32 v73, v73, v81
	v_mul_f32_e32 v69, v69, v73
	v_cvt_pk_bf16_f32 v153, v80, v69
	v_add_u32_e32 v69, s34, v78
	v_mad_i64_i32 v[80:81], s[6:7], v69, s50, v[66:67]
	v_cvt_pk_bf16_f32 v150, v86, v87
	v_cvt_pk_bf16_f32 v151, v88, v90
	v_cvt_pk_bf16_f32 v152, v92, v93
	global_store_dwordx4 v[80:81], v[150:153], off sc1
	v_or_b32_e32 v80, 4, v83
	v_cmp_gt_i32_e32 vcc, s46, v80
	v_mov_b32_e32 v107, 0
	v_mov_b32_e32 v103, 0
	v_mov_b32_e32 v98, 0
	v_mov_b32_e32 v92, 0
	v_mov_b32_e32 v86, 0
	v_mov_b32_e32 v78, 0
	v_mov_b32_e32 v69, 0
	v_mov_b32_e32 v114, 0
	v_mov_b32_e32 v111, 0
	v_mov_b32_e32 v105, 0
	v_mov_b32_e32 v101, 0
	v_mov_b32_e32 v96, 0
	v_mov_b32_e32 v90, 0
	v_mov_b32_e32 v81, 0
	v_mov_b32_e32 v73, 0
	s_and_saveexec_b64 s[6:7], vcc
	s_cbranch_execz .LBB0_1810
	v_mul_lo_u32 v1, v80, s51
	v_add3_u32 v1, 0, v1, v79
	ds_read_b128 v[150:153], v1 offset:528
	ds_read_b128 v[162:165], v1 offset:656
	s_waitcnt lgkmcnt(1)
	v_lshlrev_b32_e32 v114, 16, v150
	v_and_b32_e32 v111, 0xffff0000, v150
	v_lshlrev_b32_e32 v105, 16, v151
	v_and_b32_e32 v101, 0xffff0000, v151
	v_lshlrev_b32_e32 v96, 16, v152
	v_and_b32_e32 v90, 0xffff0000, v152
	v_lshlrev_b32_e32 v81, 16, v153
	v_and_b32_e32 v73, 0xffff0000, v153
	s_waitcnt lgkmcnt(0)
	v_lshlrev_b32_e32 v1, 16, v162
	v_and_b32_e32 v107, 0xffff0000, v162
	v_lshlrev_b32_e32 v103, 16, v163
	v_and_b32_e32 v98, 0xffff0000, v163
	v_lshlrev_b32_e32 v92, 16, v164
	v_and_b32_e32 v86, 0xffff0000, v164
	v_lshlrev_b32_e32 v78, 16, v165
	v_and_b32_e32 v69, 0xffff0000, v165
.LBB0_1810:
	s_or_b64 exec, exec, s[6:7]
	v_fma_f32 v87, v38, v129, v34
	v_fmac_f32_e32 v87, v42, v138
	v_fmac_f32_e32 v87, v50, v114
	v_mul_f32_e32 v88, 0xbfb8aa3b, v87
	v_exp_f32_e32 v88, v88
	v_fma_f32 v93, v39, v124, v35
	v_fmac_f32_e32 v93, v43, v125
	v_fmac_f32_e32 v93, v51, v111
	v_add_f32_e32 v88, 1.0, v88
	v_rcp_f32_e32 v88, v88
	v_mul_f32_e32 v94, 0xbfb8aa3b, v93
	v_exp_f32_e32 v94, v94
	v_fma_f32 v68, v46, v68, v58
	v_fmac_f32_e32 v68, v54, v127
	v_fmac_f32_e32 v68, v62, v1
	v_mul_f32_e32 v87, v87, v88
	v_mul_f32_e32 v68, v68, v87
	v_add_f32_e32 v87, 1.0, v94
	v_rcp_f32_e32 v87, v87
	v_fma_f32 v99, v41, v112, v37
	v_fmac_f32_e32 v99, v45, v113
	v_fma_f32 v88, v47, v121, v59
	v_mul_f32_e32 v87, v93, v87
	v_fma_f32 v93, v40, v118, v36
	v_fmac_f32_e32 v93, v44, v119
	v_fmac_f32_e32 v93, v52, v105
	v_mul_f32_e32 v94, 0xbfb8aa3b, v93
	v_exp_f32_e32 v94, v94
	v_fmac_f32_e32 v99, v53, v101
	v_fmac_f32_e32 v88, v55, v122
	v_mul_f32_e32 v109, 0xbfb8aa3b, v99
	v_add_f32_e32 v94, 1.0, v94
	v_rcp_f32_e32 v94, v94
	v_fmac_f32_e32 v88, v63, v107
	v_exp_f32_e32 v109, v109
	v_mul_f32_e32 v87, v88, v87
	v_fma_f32 v88, v48, v115, v60
	v_fmac_f32_e32 v88, v56, v116
	v_fmac_f32_e32 v88, v64, v103
	v_mul_f32_e32 v93, v93, v94
	v_mul_f32_e32 v88, v88, v93
	v_add_f32_e32 v93, 1.0, v109
	v_rcp_f32_e32 v93, v93
	v_fma_f32 v94, v49, v110, v61
	v_fmac_f32_e32 v94, v57, v97
	v_fma_f32 v104, v7, v104, v3
	v_mul_f32_e32 v93, v99, v93
	v_fma_f32 v99, v6, v108, v2
	v_fmac_f32_e32 v99, v10, v95
	v_fmac_f32_e32 v99, v18, v96
	v_mul_f32_e32 v108, 0xbfb8aa3b, v99
	v_exp_f32_e32 v108, v108
	v_fmac_f32_e32 v94, v65, v98
	v_fmac_f32_e32 v104, v11, v89
	v_mul_f32_e32 v93, v94, v93
	v_fma_f32 v94, v14, v106, v30
	v_add_f32_e32 v106, 1.0, v108
	v_fmac_f32_e32 v104, v19, v90
	v_rcp_f32_e32 v106, v106
	v_mul_f32_e32 v108, 0xbfb8aa3b, v104
	v_exp_f32_e32 v108, v108
	v_fmac_f32_e32 v94, v22, v91
	v_fmac_f32_e32 v94, v26, v92
	v_mul_f32_e32 v99, v99, v106
	v_mul_f32_e32 v94, v94, v99
	v_add_f32_e32 v99, 1.0, v108
	v_rcp_f32_e32 v99, v99
	v_fma_f32 v100, v8, v100, v4
	v_fmac_f32_e32 v100, v12, v84
	v_fmac_f32_e32 v100, v20, v81
	v_mul_f32_e32 v99, v104, v99
	v_mul_f32_e32 v104, 0xbfb8aa3b, v100
	v_exp_f32_e32 v104, v104
	v_fma_f32 v102, v15, v102, v31
	v_fmac_f32_e32 v102, v23, v85
	v_fma_f32 v72, v9, v72, v5
	v_fmac_f32_e32 v102, v27, v86
	v_fmac_f32_e32 v72, v13, v75
	v_mul_f32_e32 v99, v102, v99
	v_add_f32_e32 v102, 1.0, v104
	v_fmac_f32_e32 v72, v21, v73
	v_rcp_f32_e32 v102, v102
	v_mul_f32_e32 v104, 0xbfb8aa3b, v72
	v_exp_f32_e32 v104, v104
	v_fma_f32 v76, v16, v76, v32
	v_fmac_f32_e32 v76, v24, v77
	v_fmac_f32_e32 v76, v28, v78
	v_mul_f32_e32 v100, v100, v102
	v_mul_f32_e32 v76, v76, v100
	v_add_f32_e32 v100, 1.0, v104
	v_rcp_f32_e32 v100, v100
	v_fma_f32 v70, v17, v70, v33
	v_fmac_f32_e32 v70, v25, v71
	v_fmac_f32_e32 v70, v29, v69
	v_mul_f32_e32 v72, v72, v100
	v_cvt_pk_bf16_f32 v150, v68, v87
	v_add_u32_e32 v68, s34, v80
	v_mul_f32_e32 v70, v70, v72
	v_mad_i64_i32 v[108:109], s[6:7], v68, s50, v[66:67]
	v_or_b32_e32 v112, 5, v83
	v_cvt_pk_bf16_f32 v151, v88, v93
	v_cvt_pk_bf16_f32 v152, v94, v99
	v_cvt_pk_bf16_f32 v153, v76, v70
	global_store_dwordx4 v[108:109], v[150:153], off sc1
	v_cmp_gt_i32_e32 vcc, s46, v112
	v_mov_b32_e32 v106, 0
	v_mov_b32_e32 v109, 0
	v_mov_b32_e32 v104, 0
	v_mov_b32_e32 v100, 0
	v_mov_b32_e32 v94, 0
	v_mov_b32_e32 v88, 0
	v_mov_b32_e32 v80, 0
	v_mov_b32_e32 v72, 0
	v_mov_b32_e32 v68, 0
	v_mov_b32_e32 v110, 0
	v_mov_b32_e32 v108, 0
	v_mov_b32_e32 v102, 0
	v_mov_b32_e32 v99, 0
	v_mov_b32_e32 v93, 0
	v_mov_b32_e32 v87, 0
	v_mov_b32_e32 v76, 0
	v_mov_b32_e32 v70, 0
	s_and_saveexec_b64 s[6:7], vcc
	s_cbranch_execz .LBB0_1812
	v_mul_lo_u32 v68, v112, s51
	v_add3_u32 v68, 0, v68, v79
	ds_read_b128 v[150:153], v68 offset:528
	ds_read_b128 v[162:165], v68 offset:656
	s_waitcnt lgkmcnt(1)
	v_lshlrev_b32_e32 v110, 16, v150
	v_and_b32_e32 v108, 0xffff0000, v150
	v_lshlrev_b32_e32 v102, 16, v151
	v_and_b32_e32 v99, 0xffff0000, v151
	v_lshlrev_b32_e32 v93, 16, v152
	v_and_b32_e32 v87, 0xffff0000, v152
	v_lshlrev_b32_e32 v76, 16, v153
	v_and_b32_e32 v70, 0xffff0000, v153
	s_waitcnt lgkmcnt(0)
	v_lshlrev_b32_e32 v109, 16, v162
	v_and_b32_e32 v104, 0xffff0000, v162
	v_lshlrev_b32_e32 v100, 16, v163
	v_and_b32_e32 v94, 0xffff0000, v163
	v_lshlrev_b32_e32 v88, 16, v164
	v_and_b32_e32 v80, 0xffff0000, v164
	v_lshlrev_b32_e32 v72, 16, v165
	v_and_b32_e32 v68, 0xffff0000, v165
.LBB0_1812:
	s_or_b64 exec, exec, s[6:7]
	v_fma_f32 v115, v38, v138, v34
	v_fmac_f32_e32 v115, v42, v114
	v_fmac_f32_e32 v115, v50, v110
	v_mul_f32_e32 v117, 0xbfb8aa3b, v115
	v_exp_f32_e32 v117, v117
	v_fma_f32 v120, v39, v125, v35
	v_fmac_f32_e32 v120, v43, v111
	v_fmac_f32_e32 v120, v51, v108
	v_add_f32_e32 v117, 1.0, v117
	v_mul_f32_e32 v121, 0xbfb8aa3b, v120
	v_rcp_f32_e32 v117, v117
	v_exp_f32_e32 v121, v121
	v_fma_f32 v119, v40, v119, v36
	v_fmac_f32_e32 v119, v44, v105
	v_mul_f32_e32 v115, v115, v117
	v_add_f32_e32 v117, 1.0, v121
	v_rcp_f32_e32 v117, v117
	v_fma_f32 v118, v46, v127, v58
	v_fmac_f32_e32 v119, v52, v102
	v_fmac_f32_e32 v118, v54, v1
	v_mul_f32_e32 v117, v120, v117
	v_mul_f32_e32 v120, 0xbfb8aa3b, v119
	v_fmac_f32_e32 v118, v62, v109
	v_exp_f32_e32 v120, v120
	v_mul_f32_e32 v115, v118, v115
	v_fma_f32 v118, v47, v122, v59
	v_fmac_f32_e32 v118, v55, v107
	v_fma_f32 v113, v41, v113, v37
	v_fmac_f32_e32 v118, v63, v104
	v_fmac_f32_e32 v113, v45, v101
	v_mul_f32_e32 v117, v118, v117
	v_add_f32_e32 v118, 1.0, v120
	v_fmac_f32_e32 v113, v53, v99
	v_rcp_f32_e32 v118, v118
	v_mul_f32_e32 v120, 0xbfb8aa3b, v113
	v_exp_f32_e32 v120, v120
	v_fma_f32 v116, v48, v116, v60
	v_fmac_f32_e32 v116, v56, v103
	v_fmac_f32_e32 v116, v64, v100
	v_mul_f32_e32 v118, v119, v118
	v_mul_f32_e32 v118, v116, v118
	v_add_f32_e32 v116, 1.0, v120
	v_rcp_f32_e32 v116, v116
	v_fma_f32 v95, v6, v95, v2
	v_fmac_f32_e32 v95, v10, v96
	v_fmac_f32_e32 v95, v18, v93
	v_mul_f32_e32 v113, v113, v116
	v_mul_f32_e32 v116, 0xbfb8aa3b, v95
	v_exp_f32_e32 v116, v116
	v_fma_f32 v97, v49, v97, v61
	v_fmac_f32_e32 v97, v57, v98
	v_fma_f32 v89, v7, v89, v3
	v_fmac_f32_e32 v97, v65, v94
	v_fmac_f32_e32 v89, v11, v90
	v_mul_f32_e32 v97, v97, v113
	v_add_f32_e32 v113, 1.0, v116
	v_fmac_f32_e32 v89, v19, v87
	v_rcp_f32_e32 v113, v113
	v_mul_f32_e32 v116, 0xbfb8aa3b, v89
	v_exp_f32_e32 v116, v116
	v_fma_f32 v91, v14, v91, v30
	v_fmac_f32_e32 v91, v22, v92
	v_fmac_f32_e32 v91, v26, v88
	v_mul_f32_e32 v95, v95, v113
	v_mul_f32_e32 v91, v91, v95
	v_add_f32_e32 v95, 1.0, v116
	v_rcp_f32_e32 v95, v95
	v_fma_f32 v84, v8, v84, v4
	v_fmac_f32_e32 v84, v12, v81
	v_fmac_f32_e32 v84, v20, v76
	v_mul_f32_e32 v89, v89, v95
	v_mul_f32_e32 v95, 0xbfb8aa3b, v84
	v_exp_f32_e32 v95, v95
	v_fma_f32 v85, v15, v85, v31
	v_fmac_f32_e32 v85, v23, v86
	v_fma_f32 v75, v9, v75, v5
	v_fmac_f32_e32 v85, v27, v80
	v_fmac_f32_e32 v75, v13, v73
	v_mul_f32_e32 v85, v85, v89
	v_add_f32_e32 v89, 1.0, v95
	v_fmac_f32_e32 v75, v21, v70
	v_rcp_f32_e32 v89, v89
	v_mul_f32_e32 v95, 0xbfb8aa3b, v75
	v_exp_f32_e32 v95, v95
	v_fma_f32 v77, v16, v77, v32
	v_fmac_f32_e32 v77, v24, v78
	v_fmac_f32_e32 v77, v28, v72
	v_mul_f32_e32 v84, v84, v89
	v_mul_f32_e32 v77, v77, v84
	v_add_f32_e32 v84, 1.0, v95
	v_rcp_f32_e32 v84, v84
	v_fma_f32 v71, v17, v71, v33
	v_fmac_f32_e32 v71, v25, v69
	v_fmac_f32_e32 v71, v29, v68
	v_mul_f32_e32 v75, v75, v84
	v_mul_f32_e32 v71, v71, v75
	v_cvt_pk_bf16_f32 v119, v77, v71
	v_add_u32_e32 v71, s34, v112
	v_cvt_pk_bf16_f32 v116, v115, v117
	v_cvt_pk_bf16_f32 v117, v118, v97
	v_cvt_pk_bf16_f32 v118, v91, v85
	v_mad_i64_i32 v[84:85], s[6:7], v71, s50, v[66:67]
	global_store_dwordx4 v[84:85], v[116:119], off sc1
	v_mov_b32_e32 v115, 0
	v_mov_b32_e32 v112, 0
	v_or_b32_e32 v118, 6, v83
	v_cmp_gt_i32_e32 vcc, s46, v118
	v_mov_b32_e32 v95, 0
	v_mov_b32_e32 v89, 0
	v_mov_b32_e32 v84, 0
	v_mov_b32_e32 v77, 0
	v_mov_b32_e32 v71, 0
	v_mov_b32_e32 v117, 0
	v_mov_b32_e32 v116, 0
	v_mov_b32_e32 v113, 0
	v_mov_b32_e32 v97, 0
	v_mov_b32_e32 v91, 0
	v_mov_b32_e32 v85, 0
	v_mov_b32_e32 v83, 0
	v_mov_b32_e32 v75, 0
	s_and_saveexec_b64 s[6:7], vcc
	s_cbranch_execz .LBB0_1814
	v_mul_lo_u32 v71, v118, s51
	v_add3_u32 v71, 0, v71, v79
	ds_read_b128 v[120:123], v71 offset:528
	ds_read_b128 v[124:127], v71 offset:656
	s_waitcnt lgkmcnt(1)
	v_lshlrev_b32_e32 v117, 16, v120
	v_and_b32_e32 v116, 0xffff0000, v120
	v_lshlrev_b32_e32 v113, 16, v121
	v_and_b32_e32 v97, 0xffff0000, v121
	v_lshlrev_b32_e32 v91, 16, v122
	v_and_b32_e32 v85, 0xffff0000, v122
	v_lshlrev_b32_e32 v83, 16, v123
	v_and_b32_e32 v75, 0xffff0000, v123
	s_waitcnt lgkmcnt(0)
	v_lshlrev_b32_e32 v106, 16, v124
	v_and_b32_e32 v115, 0xffff0000, v124
	v_lshlrev_b32_e32 v112, 16, v125
	v_and_b32_e32 v95, 0xffff0000, v125
	v_lshlrev_b32_e32 v89, 16, v126
	v_and_b32_e32 v84, 0xffff0000, v126
	v_lshlrev_b32_e32 v77, 16, v127
	v_and_b32_e32 v71, 0xffff0000, v127
.LBB0_1814:
	s_or_b64 exec, exec, s[6:7]
	v_fma_f32 v114, v38, v114, v34
	v_fmac_f32_e32 v114, v42, v110
	v_fmac_f32_e32 v114, v50, v117
	v_mul_f32_e32 v119, 0xbfb8aa3b, v114
	v_exp_f32_e32 v119, v119
	v_fma_f32 v111, v39, v111, v35
	v_fmac_f32_e32 v111, v43, v108
	v_fmac_f32_e32 v111, v51, v116
	v_add_f32_e32 v119, 1.0, v119
	v_rcp_f32_e32 v119, v119
	v_mul_f32_e32 v120, 0xbfb8aa3b, v111
	v_exp_f32_e32 v120, v120
	v_fma_f32 v1, v46, v1, v58
	v_fmac_f32_e32 v1, v54, v109
	v_fmac_f32_e32 v1, v62, v106
	v_mul_f32_e32 v114, v114, v119
	v_mul_f32_e32 v1, v1, v114
	v_add_f32_e32 v114, 1.0, v120
	v_rcp_f32_e32 v114, v114
	v_fma_f32 v105, v40, v105, v36
	v_fmac_f32_e32 v105, v44, v102
	v_fmac_f32_e32 v105, v52, v113
	v_mul_f32_e32 v111, v111, v114
	v_mul_f32_e32 v114, 0xbfb8aa3b, v105
	v_exp_f32_e32 v114, v114
	v_fma_f32 v107, v47, v107, v59
	v_fmac_f32_e32 v107, v55, v104
	v_fma_f32 v101, v41, v101, v37
	v_fmac_f32_e32 v107, v63, v115
	v_fmac_f32_e32 v101, v45, v99
	v_mul_f32_e32 v107, v107, v111
	v_add_f32_e32 v111, 1.0, v114
	v_fmac_f32_e32 v101, v53, v97
	v_rcp_f32_e32 v111, v111
	v_mul_f32_e32 v114, 0xbfb8aa3b, v101
	v_exp_f32_e32 v114, v114
	v_fma_f32 v103, v48, v103, v60
	v_fmac_f32_e32 v103, v56, v100
	v_fmac_f32_e32 v103, v64, v112
	v_mul_f32_e32 v105, v105, v111
	v_mul_f32_e32 v103, v103, v105
	v_add_f32_e32 v105, 1.0, v114
	v_rcp_f32_e32 v105, v105
	v_fma_f32 v96, v6, v96, v2
	v_fmac_f32_e32 v96, v10, v93
	v_fmac_f32_e32 v96, v18, v91
	v_mul_f32_e32 v101, v101, v105
	v_mul_f32_e32 v105, 0xbfb8aa3b, v96
	v_exp_f32_e32 v105, v105
	v_fma_f32 v98, v49, v98, v61
	v_fmac_f32_e32 v98, v57, v94
	v_fma_f32 v90, v7, v90, v3
	v_fmac_f32_e32 v98, v65, v95
	v_fmac_f32_e32 v90, v11, v87
	v_mul_f32_e32 v98, v98, v101
	v_add_f32_e32 v101, 1.0, v105
	v_fmac_f32_e32 v90, v19, v85
	v_rcp_f32_e32 v101, v101
	v_mul_f32_e32 v105, 0xbfb8aa3b, v90
	v_exp_f32_e32 v105, v105
	v_fma_f32 v92, v14, v92, v30
	v_fmac_f32_e32 v92, v22, v88
	v_fmac_f32_e32 v92, v26, v89
	v_mul_f32_e32 v96, v96, v101
	v_mul_f32_e32 v92, v92, v96
	v_add_f32_e32 v96, 1.0, v105
	v_rcp_f32_e32 v96, v96
	v_fma_f32 v81, v8, v81, v4
	v_fmac_f32_e32 v81, v12, v76
	v_fmac_f32_e32 v81, v20, v83
	v_mul_f32_e32 v90, v90, v96
	v_mul_f32_e32 v96, 0xbfb8aa3b, v81
	v_exp_f32_e32 v96, v96
	v_fma_f32 v86, v15, v86, v31
	v_fmac_f32_e32 v86, v23, v80
	v_fma_f32 v73, v9, v73, v5
	v_fmac_f32_e32 v86, v27, v84
	v_fmac_f32_e32 v73, v13, v70
	v_mul_f32_e32 v86, v86, v90
	v_add_f32_e32 v90, 1.0, v96
	v_fmac_f32_e32 v73, v21, v75
	v_rcp_f32_e32 v90, v90
	v_mul_f32_e32 v96, 0xbfb8aa3b, v73
	v_exp_f32_e32 v96, v96
	v_fma_f32 v78, v16, v78, v32
	v_fmac_f32_e32 v78, v24, v72
	v_fmac_f32_e32 v78, v28, v77
	v_mul_f32_e32 v81, v81, v90
	v_mul_f32_e32 v78, v78, v81
	v_add_f32_e32 v81, 1.0, v96
	v_rcp_f32_e32 v81, v81
	v_fma_f32 v69, v17, v69, v33
	v_fmac_f32_e32 v69, v25, v68
	v_fmac_f32_e32 v69, v29, v71
	v_mul_f32_e32 v73, v73, v81
	v_cvt_pk_bf16_f32 v120, v1, v107
	v_add_u32_e32 v1, s34, v118
	v_mul_f32_e32 v69, v69, v73
	v_mad_i64_i32 v[118:119], s[6:7], v1, s50, v[66:67]
	v_or_b32_e32 v1, 7, v82
	v_cvt_pk_bf16_f32 v121, v103, v98
	v_cvt_pk_bf16_f32 v122, v92, v86
	v_cvt_pk_bf16_f32 v123, v78, v69
	v_cmp_gt_i32_e32 vcc, s46, v1
	v_mov_b32_e32 v107, 0
	v_mov_b32_e32 v105, 0
	v_mov_b32_e32 v98, 0
	v_mov_b32_e32 v96, 0
	v_mov_b32_e32 v86, 0
	v_mov_b32_e32 v82, 0
	v_mov_b32_e32 v73, 0
	v_mov_b32_e32 v69, 0
	v_mov_b32_e32 v114, 0
	v_mov_b32_e32 v111, 0
	v_mov_b32_e32 v103, 0
	v_mov_b32_e32 v101, 0
	v_mov_b32_e32 v92, 0
	v_mov_b32_e32 v90, 0
	v_mov_b32_e32 v81, 0
	v_mov_b32_e32 v78, 0
	global_store_dwordx4 v[118:119], v[120:123], off sc1
	s_and_saveexec_b64 s[6:7], vcc
	s_cbranch_execz .LBB0_1816
	v_mul_lo_u32 v69, v1, s51
	v_add3_u32 v69, 0, v69, v79
	ds_read_b128 v[118:121], v69 offset:528
	ds_read_b128 v[122:125], v69 offset:656
	s_waitcnt lgkmcnt(1)
	v_lshlrev_b32_e32 v114, 16, v118
	v_and_b32_e32 v111, 0xffff0000, v118
	v_lshlrev_b32_e32 v103, 16, v119
	v_and_b32_e32 v101, 0xffff0000, v119
	v_lshlrev_b32_e32 v92, 16, v120
	v_and_b32_e32 v90, 0xffff0000, v120
	v_lshlrev_b32_e32 v81, 16, v121
	v_and_b32_e32 v78, 0xffff0000, v121
	s_waitcnt lgkmcnt(0)
	v_lshlrev_b32_e32 v107, 16, v122
	v_and_b32_e32 v105, 0xffff0000, v122
	v_lshlrev_b32_e32 v98, 16, v123
	v_and_b32_e32 v96, 0xffff0000, v123
	v_lshlrev_b32_e32 v86, 16, v124
	v_and_b32_e32 v82, 0xffff0000, v124
	v_lshlrev_b32_e32 v73, 16, v125
	v_and_b32_e32 v69, 0xffff0000, v125
.LBB0_1816:
	s_or_b64 exec, exec, s[6:7]
	s_cmp_eq_u32 s36, 3
	s_cselect_b64 s[6:7], -1, 0
	v_cmp_ne_u32_e32 vcc, s46, v1
	s_or_b64 s[6:7], s[6:7], vcc
	s_or_b64 s[36:37], s[4:5], s[6:7]
	s_and_saveexec_b64 s[6:7], s[36:37]
	s_cbranch_execz .LBB0_1818
	v_fma_f32 v2, v6, v93, v2
	v_fmac_f32_e32 v2, v10, v91
	v_fmac_f32_e32 v2, v18, v92
	v_mul_f32_e32 v6, 0xbfb8aa3b, v2
	v_exp_f32_e32 v6, v6
	v_fma_f32 v34, v38, v110, v34
	v_fma_f32 v3, v7, v87, v3
	v_fmac_f32_e32 v34, v42, v117
	v_fmac_f32_e32 v3, v11, v85
	v_fmac_f32_e32 v34, v50, v114
	v_add_f32_e32 v6, 1.0, v6
	v_fmac_f32_e32 v3, v19, v90
	v_mul_f32_e32 v38, 0xbfb8aa3b, v34
	v_rcp_f32_e32 v6, v6
	v_mul_f32_e32 v7, 0xbfb8aa3b, v3
	v_exp_f32_e32 v38, v38
	v_exp_f32_e32 v7, v7
	v_fma_f32 v35, v39, v108, v35
	v_fma_f32 v14, v14, v88, v30
	v_fmac_f32_e32 v35, v43, v116
	v_fmac_f32_e32 v14, v22, v89
	v_fmac_f32_e32 v35, v51, v111
	v_fmac_f32_e32 v14, v26, v86
	v_mul_f32_e32 v2, v2, v6
	v_add_f32_e32 v38, 1.0, v38
	v_mul_f32_e32 v39, 0xbfb8aa3b, v35
	v_mul_f32_e32 v6, v14, v2
	v_add_f32_e32 v2, 1.0, v7
	v_rcp_f32_e32 v38, v38
	v_exp_f32_e32 v39, v39
	v_rcp_f32_e32 v2, v2
	v_fma_f32 v36, v40, v102, v36
	v_mul_f32_e32 v34, v34, v38
	v_add_f32_e32 v38, 1.0, v39
	v_mul_f32_e32 v2, v3, v2
	v_fma_f32 v3, v8, v76, v4
	v_rcp_f32_e32 v38, v38
	v_fmac_f32_e32 v3, v12, v83
	v_fmac_f32_e32 v3, v20, v81
	v_fmac_f32_e32 v36, v44, v113
	v_mul_f32_e32 v4, 0xbfb8aa3b, v3
	v_fmac_f32_e32 v36, v52, v103
	v_exp_f32_e32 v4, v4
	v_mul_f32_e32 v35, v35, v38
	v_mul_f32_e32 v38, 0xbfb8aa3b, v36
	v_exp_f32_e32 v38, v38
	v_fmac_f32_e32 v5, v9, v70
	v_fmac_f32_e32 v37, v41, v99
	v_fmac_f32_e32 v5, v13, v75
	v_fmac_f32_e32 v37, v45, v97
	v_fma_f32 v7, v15, v80, v31
	v_add_f32_e32 v4, 1.0, v4
	v_fmac_f32_e32 v5, v21, v78
	v_fmac_f32_e32 v37, v53, v101
	v_fmac_f32_e32 v7, v23, v84
	v_rcp_f32_e32 v4, v4
	v_mul_f32_e32 v8, 0xbfb8aa3b, v5
	v_add_f32_e32 v38, 1.0, v38
	v_mul_f32_e32 v40, 0xbfb8aa3b, v37
	v_fmac_f32_e32 v7, v27, v82
	v_exp_f32_e32 v8, v8
	v_rcp_f32_e32 v38, v38
	v_exp_f32_e32 v40, v40
	v_mul_f32_e32 v7, v7, v2
	v_fma_f32 v2, v16, v72, v32
	v_fmac_f32_e32 v2, v24, v77
	v_fmac_f32_e32 v2, v28, v73
	v_mul_f32_e32 v3, v3, v4
	v_mul_f32_e32 v9, v2, v3
	v_add_f32_e32 v2, 1.0, v8
	v_fma_f32 v39, v47, v104, v59
	v_mul_f32_e32 v36, v36, v38
	v_add_f32_e32 v38, 1.0, v40
	v_rcp_f32_e32 v2, v2
	v_fmac_f32_e32 v39, v55, v115
	v_rcp_f32_e32 v38, v38
	v_fmac_f32_e32 v39, v63, v105
	v_fmac_f32_e32 v33, v17, v68
	v_fma_f32 v42, v46, v109, v58
	v_mul_f32_e32 v35, v39, v35
	v_fma_f32 v39, v48, v100, v60
	v_fmac_f32_e32 v61, v49, v94
	v_fmac_f32_e32 v33, v25, v71
	v_fmac_f32_e32 v42, v54, v106
	v_fmac_f32_e32 v39, v56, v112
	v_fmac_f32_e32 v61, v57, v95
	v_fmac_f32_e32 v33, v29, v69
	v_mul_f32_e32 v2, v5, v2
	v_add_u32_e32 v1, s34, v1
	v_fmac_f32_e32 v42, v62, v107
	v_fmac_f32_e32 v39, v64, v98
	v_fmac_f32_e32 v61, v65, v96
	v_mul_f32_e32 v37, v37, v38
	v_mul_f32_e32 v5, v33, v2
	v_cvt_pk_bf16_f32 v4, v6, v7
	v_mad_i64_i32 v[6:7], s[36:37], v1, s50, v[66:67]
	v_mul_f32_e32 v34, v42, v34
	v_mul_f32_e32 v36, v39, v36
	v_mul_f32_e32 v10, v61, v37
	v_cvt_pk_bf16_f32 v2, v34, v35
	v_cvt_pk_bf16_f32 v3, v36, v10
	v_cvt_pk_bf16_f32 v5, v9, v5
	global_store_dwordx4 v[6:7], v[2:5], off sc1

.LBB0_1921:
	ds_read_b128 v[172:175], v4
	ds_read_b128 v[176:179], v4 offset:16896
	ds_read_b128 v[180:183], v4 offset:33792
	ds_read_b128 v[184:187], v4 offset:50688
	s_waitcnt lgkmcnt(3)
	v_lshlrev_b32_e32 v188, 16, v172
	v_and_b32_e32 v189, 0xffff0000, v172
	v_lshlrev_b32_e32 v190, 16, v173
	v_and_b32_e32 v191, 0xffff0000, v173
	v_lshlrev_b32_e32 v192, 16, v174
	v_and_b32_e32 v193, 0xffff0000, v174
	v_lshlrev_b32_e32 v194, 16, v175
	v_and_b32_e32 v195, 0xffff0000, v175
	s_waitcnt vmcnt(18)
	v_lshlrev_b32_e32 v196, 16, v26
	v_and_b32_e32 v197, 0xffff0000, v26
	v_lshlrev_b32_e32 v198, 16, v27
	v_and_b32_e32 v199, 0xffff0000, v27
	v_lshlrev_b32_e32 v200, 16, v28
	v_and_b32_e32 v201, 0xffff0000, v28
	v_lshlrev_b32_e32 v202, 16, v29
	v_and_b32_e32 v203, 0xffff0000, v29
	v_fmac_f32_e32 v196, v90, v188
	v_fmac_f32_e32 v197, v91, v189
	v_fmac_f32_e32 v198, v92, v190
	v_fmac_f32_e32 v199, v93, v191
	v_fmac_f32_e32 v200, v94, v192
	v_fmac_f32_e32 v201, v95, v193
	v_fmac_f32_e32 v202, v96, v194
	v_fmac_f32_e32 v203, v97, v195
	v_cvt_pk_bf16_f32 v26, v196, v197
	v_cvt_pk_bf16_f32 v27, v198, v199
	v_cvt_pk_bf16_f32 v28, v200, v201
	v_cvt_pk_bf16_f32 v29, v202, v203
	global_store_dwordx4 v6, v[26:29], s[6:7] sc1
	s_waitcnt lgkmcnt(2)
	v_lshlrev_b32_e32 v188, 16, v176
	v_and_b32_e32 v189, 0xffff0000, v176
	v_lshlrev_b32_e32 v190, 16, v177
	v_and_b32_e32 v191, 0xffff0000, v177
	v_lshlrev_b32_e32 v192, 16, v178
	v_and_b32_e32 v193, 0xffff0000, v178
	v_lshlrev_b32_e32 v194, 16, v179
	v_and_b32_e32 v195, 0xffff0000, v179
	v_lshlrev_b32_e32 v196, 16, v30
	v_and_b32_e32 v197, 0xffff0000, v30
	v_lshlrev_b32_e32 v198, 16, v31
	v_and_b32_e32 v199, 0xffff0000, v31
	v_lshlrev_b32_e32 v200, 16, v32
	v_and_b32_e32 v201, 0xffff0000, v32
	v_lshlrev_b32_e32 v202, 16, v33
	v_and_b32_e32 v203, 0xffff0000, v33
	v_fmac_f32_e32 v196, v90, v188
	v_fmac_f32_e32 v197, v91, v189
	v_fmac_f32_e32 v198, v92, v190
	v_fmac_f32_e32 v199, v93, v191
	v_fmac_f32_e32 v200, v94, v192
	v_fmac_f32_e32 v201, v95, v193
	v_fmac_f32_e32 v202, v96, v194
	v_fmac_f32_e32 v203, v97, v195
	v_cvt_pk_bf16_f32 v30, v196, v197
	v_cvt_pk_bf16_f32 v31, v198, v199
	v_cvt_pk_bf16_f32 v32, v200, v201
	v_cvt_pk_bf16_f32 v33, v202, v203
	global_store_dwordx4 v7, v[30:33], s[6:7] sc1
	s_waitcnt lgkmcnt(1)
	v_lshlrev_b32_e32 v188, 16, v180
	v_and_b32_e32 v189, 0xffff0000, v180
	v_lshlrev_b32_e32 v190, 16, v181
	v_and_b32_e32 v191, 0xffff0000, v181
	v_lshlrev_b32_e32 v192, 16, v182
	v_and_b32_e32 v193, 0xffff0000, v182
	v_lshlrev_b32_e32 v194, 16, v183
	v_and_b32_e32 v195, 0xffff0000, v183
	v_lshlrev_b32_e32 v196, 16, v34
	v_and_b32_e32 v197, 0xffff0000, v34
	v_lshlrev_b32_e32 v198, 16, v35
	v_and_b32_e32 v199, 0xffff0000, v35
	v_lshlrev_b32_e32 v200, 16, v36
	v_and_b32_e32 v201, 0xffff0000, v36
	v_lshlrev_b32_e32 v202, 16, v37
	v_and_b32_e32 v203, 0xffff0000, v37
	v_fmac_f32_e32 v196, v90, v188
	v_fmac_f32_e32 v197, v91, v189
	v_fmac_f32_e32 v198, v92, v190
	v_fmac_f32_e32 v199, v93, v191
	v_fmac_f32_e32 v200, v94, v192
	v_fmac_f32_e32 v201, v95, v193
	v_fmac_f32_e32 v202, v96, v194
	v_fmac_f32_e32 v203, v97, v195
	v_cvt_pk_bf16_f32 v34, v196, v197
	v_cvt_pk_bf16_f32 v35, v198, v199
	v_cvt_pk_bf16_f32 v36, v200, v201
	v_cvt_pk_bf16_f32 v37, v202, v203
	global_store_dwordx4 v8, v[34:37], s[6:7] sc1
	s_waitcnt lgkmcnt(0)
	v_lshlrev_b32_e32 v188, 16, v184
	v_and_b32_e32 v189, 0xffff0000, v184
	v_lshlrev_b32_e32 v190, 16, v185
	v_and_b32_e32 v191, 0xffff0000, v185
	v_lshlrev_b32_e32 v192, 16, v186
	v_and_b32_e32 v193, 0xffff0000, v186
	v_lshlrev_b32_e32 v194, 16, v187
	v_and_b32_e32 v195, 0xffff0000, v187
	ds_read_b128 v[172:175], v4 offset:256
	ds_read_b128 v[176:179], v4 offset:17152
	ds_read_b128 v[180:183], v4 offset:34048
	ds_read_b128 v[184:187], v4 offset:50944
	v_lshlrev_b32_e32 v196, 16, v38
	v_and_b32_e32 v197, 0xffff0000, v38
	v_lshlrev_b32_e32 v198, 16, v39
	v_and_b32_e32 v199, 0xffff0000, v39
	v_lshlrev_b32_e32 v200, 16, v40
	v_and_b32_e32 v201, 0xffff0000, v40
	v_lshlrev_b32_e32 v202, 16, v41
	v_and_b32_e32 v203, 0xffff0000, v41
	v_fmac_f32_e32 v196, v90, v188
	v_fmac_f32_e32 v197, v91, v189
	v_fmac_f32_e32 v198, v92, v190
	v_fmac_f32_e32 v199, v93, v191
	v_fmac_f32_e32 v200, v94, v192
	v_fmac_f32_e32 v201, v95, v193
	v_fmac_f32_e32 v202, v96, v194
	v_fmac_f32_e32 v203, v97, v195
	v_cvt_pk_bf16_f32 v38, v196, v197
	v_cvt_pk_bf16_f32 v39, v198, v199
	v_cvt_pk_bf16_f32 v40, v200, v201
	v_cvt_pk_bf16_f32 v41, v202, v203
	global_store_dwordx4 v9, v[38:41], s[6:7] sc1
	s_waitcnt lgkmcnt(3)
	v_lshlrev_b32_e32 v188, 16, v172
	v_and_b32_e32 v189, 0xffff0000, v172
	v_lshlrev_b32_e32 v190, 16, v173
	v_and_b32_e32 v191, 0xffff0000, v173
	v_lshlrev_b32_e32 v192, 16, v174
	v_and_b32_e32 v193, 0xffff0000, v174
	v_lshlrev_b32_e32 v194, 16, v175
	v_and_b32_e32 v195, 0xffff0000, v175
	s_waitcnt vmcnt(16)
	v_lshlrev_b32_e32 v196, 16, v42
	v_and_b32_e32 v197, 0xffff0000, v42
	v_lshlrev_b32_e32 v198, 16, v43
	v_and_b32_e32 v199, 0xffff0000, v43
	v_lshlrev_b32_e32 v200, 16, v44
	v_and_b32_e32 v201, 0xffff0000, v44
	v_lshlrev_b32_e32 v202, 16, v45
	v_and_b32_e32 v203, 0xffff0000, v45
	v_fmac_f32_e32 v196, v98, v188
	v_fmac_f32_e32 v197, v99, v189
	v_fmac_f32_e32 v198, v100, v190
	v_fmac_f32_e32 v199, v101, v191
	v_fmac_f32_e32 v200, v102, v192
	v_fmac_f32_e32 v201, v103, v193
	v_fmac_f32_e32 v202, v104, v194
	v_fmac_f32_e32 v203, v105, v195
	v_cvt_pk_bf16_f32 v42, v196, v197
	v_cvt_pk_bf16_f32 v43, v198, v199
	v_cvt_pk_bf16_f32 v44, v200, v201
	v_cvt_pk_bf16_f32 v45, v202, v203
	global_store_dwordx4 v10, v[42:45], s[6:7] sc1
	s_waitcnt lgkmcnt(2)
	v_lshlrev_b32_e32 v188, 16, v176
	v_and_b32_e32 v189, 0xffff0000, v176
	v_lshlrev_b32_e32 v190, 16, v177
	v_and_b32_e32 v191, 0xffff0000, v177
	v_lshlrev_b32_e32 v192, 16, v178
	v_and_b32_e32 v193, 0xffff0000, v178
	v_lshlrev_b32_e32 v194, 16, v179
	v_and_b32_e32 v195, 0xffff0000, v179
	v_lshlrev_b32_e32 v196, 16, v46
	v_and_b32_e32 v197, 0xffff0000, v46
	v_lshlrev_b32_e32 v198, 16, v47
	v_and_b32_e32 v199, 0xffff0000, v47
	v_lshlrev_b32_e32 v200, 16, v48
	v_and_b32_e32 v201, 0xffff0000, v48
	v_lshlrev_b32_e32 v202, 16, v49
	v_and_b32_e32 v203, 0xffff0000, v49
	v_fmac_f32_e32 v196, v98, v188
	v_fmac_f32_e32 v197, v99, v189
	v_fmac_f32_e32 v198, v100, v190
	v_fmac_f32_e32 v199, v101, v191
	v_fmac_f32_e32 v200, v102, v192
	v_fmac_f32_e32 v201, v103, v193
	v_fmac_f32_e32 v202, v104, v194
	v_fmac_f32_e32 v203, v105, v195
	v_cvt_pk_bf16_f32 v46, v196, v197
	v_cvt_pk_bf16_f32 v47, v198, v199
	v_cvt_pk_bf16_f32 v48, v200, v201
	v_cvt_pk_bf16_f32 v49, v202, v203
	global_store_dwordx4 v11, v[46:49], s[6:7] sc1
	s_waitcnt lgkmcnt(1)
	v_lshlrev_b32_e32 v188, 16, v180
	v_and_b32_e32 v189, 0xffff0000, v180
	v_lshlrev_b32_e32 v190, 16, v181
	v_and_b32_e32 v191, 0xffff0000, v181
	v_lshlrev_b32_e32 v192, 16, v182
	v_and_b32_e32 v193, 0xffff0000, v182
	v_lshlrev_b32_e32 v194, 16, v183
	v_and_b32_e32 v195, 0xffff0000, v183
	v_lshlrev_b32_e32 v196, 16, v50
	v_and_b32_e32 v197, 0xffff0000, v50
	v_lshlrev_b32_e32 v198, 16, v51
	v_and_b32_e32 v199, 0xffff0000, v51
	v_lshlrev_b32_e32 v200, 16, v52
	v_and_b32_e32 v201, 0xffff0000, v52
	v_lshlrev_b32_e32 v202, 16, v53
	v_and_b32_e32 v203, 0xffff0000, v53
	v_fmac_f32_e32 v196, v98, v188
	v_fmac_f32_e32 v197, v99, v189
	v_fmac_f32_e32 v198, v100, v190
	v_fmac_f32_e32 v199, v101, v191
	v_fmac_f32_e32 v200, v102, v192
	v_fmac_f32_e32 v201, v103, v193
	v_fmac_f32_e32 v202, v104, v194
	v_fmac_f32_e32 v203, v105, v195
	v_cvt_pk_bf16_f32 v50, v196, v197
	v_cvt_pk_bf16_f32 v51, v198, v199
	v_cvt_pk_bf16_f32 v52, v200, v201
	v_cvt_pk_bf16_f32 v53, v202, v203
	global_store_dwordx4 v12, v[50:53], s[6:7] sc1
	s_waitcnt lgkmcnt(0)
	v_lshlrev_b32_e32 v188, 16, v184
	v_and_b32_e32 v189, 0xffff0000, v184
	v_lshlrev_b32_e32 v190, 16, v185
	v_and_b32_e32 v191, 0xffff0000, v185
	v_lshlrev_b32_e32 v192, 16, v186
	v_and_b32_e32 v193, 0xffff0000, v186
	v_lshlrev_b32_e32 v194, 16, v187
	v_and_b32_e32 v195, 0xffff0000, v187
	ds_read_b128 v[172:175], v5
	ds_read_b128 v[176:179], v5 offset:16896
	ds_read_b128 v[180:183], v5 offset:33792
	ds_read_b128 v[184:187], v5 offset:50688
	v_lshlrev_b32_e32 v196, 16, v54
	v_and_b32_e32 v197, 0xffff0000, v54
	v_lshlrev_b32_e32 v198, 16, v55
	v_and_b32_e32 v199, 0xffff0000, v55
	v_lshlrev_b32_e32 v200, 16, v56
	v_and_b32_e32 v201, 0xffff0000, v56
	v_lshlrev_b32_e32 v202, 16, v57
	v_and_b32_e32 v203, 0xffff0000, v57
	v_fmac_f32_e32 v196, v98, v188
	v_fmac_f32_e32 v197, v99, v189
	v_fmac_f32_e32 v198, v100, v190
	v_fmac_f32_e32 v199, v101, v191
	v_fmac_f32_e32 v200, v102, v192
	v_fmac_f32_e32 v201, v103, v193
	v_fmac_f32_e32 v202, v104, v194
	v_fmac_f32_e32 v203, v105, v195
	v_cvt_pk_bf16_f32 v54, v196, v197
	v_cvt_pk_bf16_f32 v55, v198, v199
	v_cvt_pk_bf16_f32 v56, v200, v201
	v_cvt_pk_bf16_f32 v57, v202, v203
	global_store_dwordx4 v13, v[54:57], s[6:7] sc1
	s_waitcnt lgkmcnt(3)
	v_lshlrev_b32_e32 v188, 16, v172
	v_and_b32_e32 v189, 0xffff0000, v172
	v_lshlrev_b32_e32 v190, 16, v173
	v_and_b32_e32 v191, 0xffff0000, v173
	v_lshlrev_b32_e32 v192, 16, v174
	v_and_b32_e32 v193, 0xffff0000, v174
	v_lshlrev_b32_e32 v194, 16, v175
	v_and_b32_e32 v195, 0xffff0000, v175
	s_waitcnt vmcnt(14)
	v_lshlrev_b32_e32 v196, 16, v58
	v_and_b32_e32 v197, 0xffff0000, v58
	v_lshlrev_b32_e32 v198, 16, v59
	v_and_b32_e32 v199, 0xffff0000, v59
	v_lshlrev_b32_e32 v200, 16, v60
	v_and_b32_e32 v201, 0xffff0000, v60
	v_lshlrev_b32_e32 v202, 16, v61
	v_and_b32_e32 v203, 0xffff0000, v61
	v_fmac_f32_e32 v196, v106, v188
	v_fmac_f32_e32 v197, v107, v189
	v_fmac_f32_e32 v198, v108, v190
	v_fmac_f32_e32 v199, v109, v191
	v_fmac_f32_e32 v200, v110, v192
	v_fmac_f32_e32 v201, v111, v193
	v_fmac_f32_e32 v202, v112, v194
	v_fmac_f32_e32 v203, v113, v195
	v_cvt_pk_bf16_f32 v58, v196, v197
	v_cvt_pk_bf16_f32 v59, v198, v199
	v_cvt_pk_bf16_f32 v60, v200, v201
	v_cvt_pk_bf16_f32 v61, v202, v203
	global_store_dwordx4 v14, v[58:61], s[6:7] sc1
	s_waitcnt lgkmcnt(2)
	v_lshlrev_b32_e32 v188, 16, v176
	v_and_b32_e32 v189, 0xffff0000, v176
	v_lshlrev_b32_e32 v190, 16, v177
	v_and_b32_e32 v191, 0xffff0000, v177
	v_lshlrev_b32_e32 v192, 16, v178
	v_and_b32_e32 v193, 0xffff0000, v178
	v_lshlrev_b32_e32 v194, 16, v179
	v_and_b32_e32 v195, 0xffff0000, v179
	v_lshlrev_b32_e32 v196, 16, v62
	v_and_b32_e32 v197, 0xffff0000, v62
	v_lshlrev_b32_e32 v198, 16, v63
	v_and_b32_e32 v199, 0xffff0000, v63
	v_lshlrev_b32_e32 v200, 16, v64
	v_and_b32_e32 v201, 0xffff0000, v64
	v_lshlrev_b32_e32 v202, 16, v65
	v_and_b32_e32 v203, 0xffff0000, v65
	v_fmac_f32_e32 v196, v106, v188
	v_fmac_f32_e32 v197, v107, v189
	v_fmac_f32_e32 v198, v108, v190
	v_fmac_f32_e32 v199, v109, v191
	v_fmac_f32_e32 v200, v110, v192
	v_fmac_f32_e32 v201, v111, v193
	v_fmac_f32_e32 v202, v112, v194
	v_fmac_f32_e32 v203, v113, v195
	v_cvt_pk_bf16_f32 v62, v196, v197
	v_cvt_pk_bf16_f32 v63, v198, v199
	v_cvt_pk_bf16_f32 v64, v200, v201
	v_cvt_pk_bf16_f32 v65, v202, v203
	global_store_dwordx4 v15, v[62:65], s[6:7] sc1
	s_waitcnt lgkmcnt(1)
	v_lshlrev_b32_e32 v188, 16, v180
	v_and_b32_e32 v189, 0xffff0000, v180
	v_lshlrev_b32_e32 v190, 16, v181
	v_and_b32_e32 v191, 0xffff0000, v181
	v_lshlrev_b32_e32 v192, 16, v182
	v_and_b32_e32 v193, 0xffff0000, v182
	v_lshlrev_b32_e32 v194, 16, v183
	v_and_b32_e32 v195, 0xffff0000, v183
	v_lshlrev_b32_e32 v196, 16, v66
	v_and_b32_e32 v197, 0xffff0000, v66
	v_lshlrev_b32_e32 v198, 16, v67
	v_and_b32_e32 v199, 0xffff0000, v67
	v_lshlrev_b32_e32 v200, 16, v68
	v_and_b32_e32 v201, 0xffff0000, v68
	v_lshlrev_b32_e32 v202, 16, v69
	v_and_b32_e32 v203, 0xffff0000, v69
	v_fmac_f32_e32 v196, v106, v188
	v_fmac_f32_e32 v197, v107, v189
	v_fmac_f32_e32 v198, v108, v190
	v_fmac_f32_e32 v199, v109, v191
	v_fmac_f32_e32 v200, v110, v192
	v_fmac_f32_e32 v201, v111, v193
	v_fmac_f32_e32 v202, v112, v194
	v_fmac_f32_e32 v203, v113, v195
	v_cvt_pk_bf16_f32 v66, v196, v197
	v_cvt_pk_bf16_f32 v67, v198, v199
	v_cvt_pk_bf16_f32 v68, v200, v201
	v_cvt_pk_bf16_f32 v69, v202, v203
	global_store_dwordx4 v16, v[66:69], s[6:7] sc1
	s_waitcnt lgkmcnt(0)
	v_lshlrev_b32_e32 v188, 16, v184
	v_and_b32_e32 v189, 0xffff0000, v184
	v_lshlrev_b32_e32 v190, 16, v185
	v_and_b32_e32 v191, 0xffff0000, v185
	v_lshlrev_b32_e32 v192, 16, v186
	v_and_b32_e32 v193, 0xffff0000, v186
	v_lshlrev_b32_e32 v194, 16, v187
	v_and_b32_e32 v195, 0xffff0000, v187
	ds_read_b128 v[172:175], v5 offset:256
	ds_read_b128 v[176:179], v5 offset:17152
	ds_read_b128 v[180:183], v5 offset:34048
	ds_read_b128 v[184:187], v5 offset:50944
	v_lshlrev_b32_e32 v196, 16, v70
	v_and_b32_e32 v197, 0xffff0000, v70
	v_lshlrev_b32_e32 v198, 16, v71
	v_and_b32_e32 v199, 0xffff0000, v71
	v_lshlrev_b32_e32 v200, 16, v72
	v_and_b32_e32 v201, 0xffff0000, v72
	v_lshlrev_b32_e32 v202, 16, v73
	v_and_b32_e32 v203, 0xffff0000, v73
	v_fmac_f32_e32 v196, v106, v188
	v_fmac_f32_e32 v197, v107, v189
	v_fmac_f32_e32 v198, v108, v190
	v_fmac_f32_e32 v199, v109, v191
	v_fmac_f32_e32 v200, v110, v192
	v_fmac_f32_e32 v201, v111, v193
	v_fmac_f32_e32 v202, v112, v194
	v_fmac_f32_e32 v203, v113, v195
	v_cvt_pk_bf16_f32 v70, v196, v197
	v_cvt_pk_bf16_f32 v71, v198, v199
	v_cvt_pk_bf16_f32 v72, v200, v201
	v_cvt_pk_bf16_f32 v73, v202, v203
	global_store_dwordx4 v17, v[70:73], s[6:7] sc1
	s_waitcnt lgkmcnt(3)
	v_lshlrev_b32_e32 v188, 16, v172
	v_and_b32_e32 v189, 0xffff0000, v172
	v_lshlrev_b32_e32 v190, 16, v173
	v_and_b32_e32 v191, 0xffff0000, v173
	v_lshlrev_b32_e32 v192, 16, v174
	v_and_b32_e32 v193, 0xffff0000, v174
	v_lshlrev_b32_e32 v194, 16, v175
	v_and_b32_e32 v195, 0xffff0000, v175
	s_waitcnt vmcnt(12)
	v_lshlrev_b32_e32 v196, 16, v74
	v_and_b32_e32 v197, 0xffff0000, v74
	v_lshlrev_b32_e32 v198, 16, v75
	v_and_b32_e32 v199, 0xffff0000, v75
	v_lshlrev_b32_e32 v200, 16, v76
	v_and_b32_e32 v201, 0xffff0000, v76
	v_lshlrev_b32_e32 v202, 16, v77
	v_and_b32_e32 v203, 0xffff0000, v77
	v_fmac_f32_e32 v196, v114, v188
	v_fmac_f32_e32 v197, v115, v189
	v_fmac_f32_e32 v198, v116, v190
	v_fmac_f32_e32 v199, v117, v191
	v_fmac_f32_e32 v200, v118, v192
	v_fmac_f32_e32 v201, v119, v193
	v_fmac_f32_e32 v202, v120, v194
	v_fmac_f32_e32 v203, v121, v195
	v_cvt_pk_bf16_f32 v74, v196, v197
	v_cvt_pk_bf16_f32 v75, v198, v199
	v_cvt_pk_bf16_f32 v76, v200, v201
	v_cvt_pk_bf16_f32 v77, v202, v203
	global_store_dwordx4 v18, v[74:77], s[6:7] sc1
	s_waitcnt lgkmcnt(2)
	v_lshlrev_b32_e32 v188, 16, v176
	v_and_b32_e32 v189, 0xffff0000, v176
	v_lshlrev_b32_e32 v190, 16, v177
	v_and_b32_e32 v191, 0xffff0000, v177
	v_lshlrev_b32_e32 v192, 16, v178
	v_and_b32_e32 v193, 0xffff0000, v178
	v_lshlrev_b32_e32 v194, 16, v179
	v_and_b32_e32 v195, 0xffff0000, v179
	v_lshlrev_b32_e32 v196, 16, v78
	v_and_b32_e32 v197, 0xffff0000, v78
	v_lshlrev_b32_e32 v198, 16, v79
	v_and_b32_e32 v199, 0xffff0000, v79
	v_lshlrev_b32_e32 v200, 16, v80
	v_and_b32_e32 v201, 0xffff0000, v80
	v_lshlrev_b32_e32 v202, 16, v81
	v_and_b32_e32 v203, 0xffff0000, v81
	v_fmac_f32_e32 v196, v114, v188
	v_fmac_f32_e32 v197, v115, v189
	v_fmac_f32_e32 v198, v116, v190
	v_fmac_f32_e32 v199, v117, v191
	v_fmac_f32_e32 v200, v118, v192
	v_fmac_f32_e32 v201, v119, v193
	v_fmac_f32_e32 v202, v120, v194
	v_fmac_f32_e32 v203, v121, v195
	v_cvt_pk_bf16_f32 v78, v196, v197
	v_cvt_pk_bf16_f32 v79, v198, v199
	v_cvt_pk_bf16_f32 v80, v200, v201
	v_cvt_pk_bf16_f32 v81, v202, v203
	global_store_dwordx4 v19, v[78:81], s[6:7] sc1
	s_waitcnt lgkmcnt(1)
	v_lshlrev_b32_e32 v188, 16, v180
	v_and_b32_e32 v189, 0xffff0000, v180
	v_lshlrev_b32_e32 v190, 16, v181
	v_and_b32_e32 v191, 0xffff0000, v181
	v_lshlrev_b32_e32 v192, 16, v182
	v_and_b32_e32 v193, 0xffff0000, v182
	v_lshlrev_b32_e32 v194, 16, v183
	v_and_b32_e32 v195, 0xffff0000, v183
	v_lshlrev_b32_e32 v196, 16, v82
	v_and_b32_e32 v197, 0xffff0000, v82
	v_lshlrev_b32_e32 v198, 16, v83
	v_and_b32_e32 v199, 0xffff0000, v83
	v_lshlrev_b32_e32 v200, 16, v84
	v_and_b32_e32 v201, 0xffff0000, v84
	v_lshlrev_b32_e32 v202, 16, v85
	v_and_b32_e32 v203, 0xffff0000, v85
	v_fmac_f32_e32 v196, v114, v188
	v_fmac_f32_e32 v197, v115, v189
	v_fmac_f32_e32 v198, v116, v190
	v_fmac_f32_e32 v199, v117, v191
	v_fmac_f32_e32 v200, v118, v192
	v_fmac_f32_e32 v201, v119, v193
	v_fmac_f32_e32 v202, v120, v194
	v_fmac_f32_e32 v203, v121, v195
	v_cvt_pk_bf16_f32 v82, v196, v197
	v_cvt_pk_bf16_f32 v83, v198, v199
	v_cvt_pk_bf16_f32 v84, v200, v201
	v_cvt_pk_bf16_f32 v85, v202, v203
	global_store_dwordx4 v20, v[82:85], s[6:7] sc1
	s_waitcnt lgkmcnt(0)
	v_lshlrev_b32_e32 v188, 16, v184
	v_and_b32_e32 v189, 0xffff0000, v184
	v_lshlrev_b32_e32 v190, 16, v185
	v_and_b32_e32 v191, 0xffff0000, v185
	v_lshlrev_b32_e32 v192, 16, v186
	v_and_b32_e32 v193, 0xffff0000, v186
	v_lshlrev_b32_e32 v194, 16, v187
	v_and_b32_e32 v195, 0xffff0000, v187
	v_lshlrev_b32_e32 v196, 16, v86
	v_and_b32_e32 v197, 0xffff0000, v86
	v_lshlrev_b32_e32 v198, 16, v87
	v_and_b32_e32 v199, 0xffff0000, v87
	v_lshlrev_b32_e32 v200, 16, v88
	v_and_b32_e32 v201, 0xffff0000, v88
	v_lshlrev_b32_e32 v202, 16, v89
	v_and_b32_e32 v203, 0xffff0000, v89
	v_fmac_f32_e32 v196, v114, v188
	v_fmac_f32_e32 v197, v115, v189
	v_fmac_f32_e32 v198, v116, v190
	v_fmac_f32_e32 v199, v117, v191
	v_fmac_f32_e32 v200, v118, v192
	v_fmac_f32_e32 v201, v119, v193
	v_fmac_f32_e32 v202, v120, v194
	v_fmac_f32_e32 v203, v121, v195
	v_cvt_pk_bf16_f32 v86, v196, v197
	v_cvt_pk_bf16_f32 v87, v198, v199
	v_cvt_pk_bf16_f32 v88, v200, v201
	v_cvt_pk_bf16_f32 v89, v202, v203
	global_store_dwordx4 v21, v[86:89], s[6:7] sc1
	s_mov_b64 s[4:5], 0
	s_barrier
	s_branch .LBB0_1883
